# p4_loghoist: P4 ret unit issues both decay loads and the 13 q/k/state loads before the log_sigmoid arithmetic (renamed temps), second unit reuses the two results via SGPRs; on top of v6
# speedup vs baseline: 1.0076x; 1.0023x over previous
; #define LAS __attribute__((address_space(3)))
; __device__ __forceinline__ float fexp2(float x) { return __builtin_amdgcn_exp2f(x); }
; __device__ __forceinline__ float log_sigmoid(float x) { return -log1pf(expf(-x)); }
; __device__ __forceinline__ void ret_unit(LAS unsigned char* lds, int u, const bf16* PROJ, const int* pos, const float* dec_f, const float* dec_b, const bf16* ST,
;                                          const float* gn_w, const float* gn_b, bf16* MIX, int tid, const WsRef& wsr) {
;     const int lane = tid & 63, wave = tid >> 6, fr = lane & 15, fq = lane >> 4;
;     const int bh = u >> 6, c = u & 63, b = bh >> 2, h = bh & 3;
;     const size_t row0 = (size_t)b * SEQ + (size_t)c * 128;
;     LAS bf16* Qs = (LAS bf16*)lds; LAS bf16* Ks = (LAS bf16*)(lds + TILE_B); LAS bf16* VT = (LAS bf16*)(lds + 2 * TILE_B);
;     const float lgf2 = log_sigmoid(dec_f[h]) * LOG2E, lgb2 = log_sigmoid(dec_b[h]) * LOG2E;
;     ...
; #pragma unroll
;     for (int n = 0; n < 8; ++n) {
; #pragma unroll
;         for (int r = 0; r < 4; ++r) { const int key = n * 16 + 4 * fq + r; const int df = q - key; const float f = df >= 0 ? fexp2(lgf2 * (float)df) : fexp2(lgb2 * (float)(-df)); s[n][r] *= f; } }
.LBB0_435:
	s_cmp_lt_i32 s86, 5
	s_cselect_b64 s[4:5], -1, 0
	s_and_b64 s[4:5], s[4:5], s[0:1]
	s_andn2_b64 vcc, exec, s[4:5]
	s_cbranch_vccnz .LBB0_440
	s_cmpk_gt_i32 s2, 0x1ff
	s_cbranch_scc1 .LBB0_440
	v_and_b32_e32 v6, 7, v128
	v_lshlrev_b32_e32 v7, 3, v6
	v_cvt_f32_ubyte0_e32 v8, v7
	v_mul_f32_e32 v8, 0xbe549a78, v8
	v_exp_f32_e32 v107, v8
	v_or_b32_e32 v8, 1, v7
	v_cvt_f32_ubyte0_e32 v8, v8
	v_mul_f32_e32 v8, 0xbe549a78, v8
	v_exp_f32_e32 v108, v8
	v_or_b32_e32 v8, 2, v7
	v_cvt_f32_ubyte0_e32 v8, v8
	v_mul_f32_e32 v8, 0xbe549a78, v8
	v_exp_f32_e32 v109, v8
	v_or_b32_e32 v8, 3, v7
	v_cvt_f32_ubyte0_e32 v8, v8
	v_mul_f32_e32 v8, 0xbe549a78, v8
	v_exp_f32_e32 v110, v8
	v_or_b32_e32 v8, 4, v7
	v_cvt_f32_ubyte0_e32 v8, v8
	v_mul_f32_e32 v8, 0xbe549a78, v8
	v_exp_f32_e32 v111, v8
	v_or_b32_e32 v8, 5, v7
	v_cvt_f32_ubyte0_e32 v8, v8
	v_mul_f32_e32 v8, 0xbe549a78, v8
	v_exp_f32_e32 v112, v8
	v_or_b32_e32 v8, 6, v7
	v_or_b32_e32 v7, 7, v7
	v_cvt_f32_ubyte0_e32 v7, v7
	v_lshrrev_b32_e32 v98, 3, v128
	v_mul_f32_e32 v7, 0xbe549a78, v7
	v_add_u32_e32 v1, 0x200, v128
	v_exp_f32_e32 v114, v7
	v_mul_u32_u24_e32 v7, 0x88, v98
	v_lshrrev_b32_e32 v100, 3, v1
	v_lshlrev_b32_e32 v7, 1, v7
	v_lshlrev_b32_e32 v6, 4, v6
	v_cvt_f32_ubyte0_e32 v8, v8
	v_add3_u32 v115, 0, v7, v6
	v_mul_u32_u24_e32 v7, 0x88, v100
	v_lshlrev_b32_e32 v4, 3, v128
	v_mul_f32_e32 v8, 0xbe549a78, v8
	v_lshlrev_b32_e32 v7, 1, v7
	v_lshrrev_b32_e32 v117, 4, v1
	s_add_i32 s0, 0, 0x11000
	v_lshrrev_b32_e32 v1, 7, v1
	v_and_b32_e32 v106, 56, v4
	v_exp_f32_e32 v113, v8
	v_add3_u32 v116, 0, v7, v6
	v_and_b32_e32 v4, 0x78, v4
	s_movk_i32 s1, 0x110
	v_mov_b32_e32 v7, s0
	v_and_b32_e32 v8, 14, v98
	v_bitop3_b32 v1, v1, v128, 7 bitop3:0x78
	v_or_b32_e32 v0, 0x400, v128
	v_mad_u32_u24 v7, v4, s1, v7
	v_lshl_or_b32 v1, v1, 4, v8
	v_add_u32_e32 v121, v7, v1
	v_lshrrev_b32_e32 v1, 7, v0
	v_bitop3_b32 v1, v1, v128, 7 bitop3:0x78
	v_add_u32_e32 v2, 0x600, v128
	v_lshl_or_b32 v1, v1, 4, v8
	v_add_u32_e32 v122, v7, v1
	v_lshrrev_b32_e32 v1, 7, v2
	v_bitop3_b32 v1, v1, v128, 7 bitop3:0x78
	v_writelane_b32 v255, s4, 38
	v_lshrrev_b32_e32 v6, 7, v128
	v_lshl_or_b32 v1, v1, 4, v8
	v_writelane_b32 v255, s5, 39
	v_and_b32_e32 v3, 15, v128
	v_bfe_u32 v5, v128, 4, 2
	v_bitop3_b32 v6, v6, v128, 7 bitop3:0x78
	v_add_u32_e32 v123, v7, v1
	v_lshrrev_b32_e32 v1, 2, v128
	s_movk_i32 s3, 0xf0
	v_writelane_b32 v255, s82, 40
	v_lshl_or_b32 v6, v6, 4, v8
	v_and_or_b32 v102, v1, s3, v3
	v_lshlrev_b32_e32 v126, 2, v5
	v_writelane_b32 v255, s83, 41
	v_lshrrev_b32_e32 v119, 4, v2
	v_add_u32_e32 v120, v7, v6
	v_lshlrev_b32_e32 v2, 4, v5
	v_mov_b32_e32 v7, 0x5500
	v_sub_u32_e32 v5, v102, v126
	v_writelane_b32 v255, s80, 42
	v_mad_u32_u24 v125, v3, s1, v7
	v_sub_u32_e32 v7, 0, v5
	v_writelane_b32 v255, s81, 43
	v_max_i32_e32 v7, v5, v7
	v_cmp_gt_i32_e64 s[4:5], 0, v5
	v_xad_u32 v5, v126, -1, v102
	v_cvt_f32_u32_e32 v127, v7
	v_writelane_b32 v255, s4, 44
	v_sub_u32_e32 v7, 0, v5
	v_max_i32_e32 v7, v5, v7
	v_writelane_b32 v255, s5, 45
	v_cmp_gt_i32_e64 s[4:5], 0, v5
	v_or_b32_e32 v5, 2, v126
	v_sub_u32_e32 v5, v102, v5
	v_writelane_b32 v255, s4, 46
	v_cvt_f32_u32_e32 v129, v7
	v_sub_u32_e32 v7, 0, v5
	v_writelane_b32 v255, s5, 47
	v_max_i32_e32 v7, v5, v7
	v_cmp_gt_i32_e64 s[4:5], 0, v5
	v_or_b32_e32 v5, 3, v126
	v_sub_u32_e32 v5, v102, v5
	v_cvt_f32_u32_e32 v231, v7
	v_sub_u32_e32 v7, 0, v5
	v_max_i32_e32 v7, v5, v7
	v_cmp_gt_i32_e64 s[82:83], 0, v5
	v_or_b32_e32 v5, 16, v126
	v_sub_u32_e32 v5, v102, v5
	v_cvt_f32_u32_e32 v252, v7
	v_sub_u32_e32 v7, 0, v5
	v_max_i32_e32 v7, v5, v7
	v_cmp_gt_i32_e64 s[80:81], 0, v5
	v_or_b32_e32 v5, 17, v126
	v_sub_u32_e32 v5, v102, v5
	v_writelane_b32 v255, s4, 48
	v_cvt_f32_u32_e32 v253, v7
	v_sub_u32_e32 v7, 0, v5
	v_writelane_b32 v255, s5, 49
	v_max_i32_e32 v7, v5, v7
	v_cmp_gt_i32_e64 s[4:5], 0, v5
	v_or_b32_e32 v5, 18, v126
	v_sub_u32_e32 v5, v102, v5
	v_cvt_f32_u32_e32 v254, v7
	v_sub_u32_e32 v7, 0, v5
	v_max_i32_e32 v7, v5, v7
	v_cmp_gt_i32_e64 s[66:67], 0, v5
	v_or_b32_e32 v5, 19, v126
	v_sub_u32_e32 v5, v102, v5
	v_cvt_f32_u32_e32 v134, v7
	v_sub_u32_e32 v7, 0, v5
	v_max_i32_e32 v7, v5, v7
	v_cmp_gt_i32_e64 s[26:27], 0, v5
	v_or_b32_e32 v5, 32, v126
	v_sub_u32_e32 v5, v102, v5
	v_cvt_f32_u32_e32 v135, v7
	v_sub_u32_e32 v7, 0, v5
	v_max_i32_e32 v7, v5, v7
	v_cmp_gt_i32_e64 s[28:29], 0, v5
	v_or_b32_e32 v5, 33, v126
	v_sub_u32_e32 v5, v102, v5
	v_cvt_f32_u32_e32 v136, v7
	v_sub_u32_e32 v7, 0, v5
	v_max_i32_e32 v7, v5, v7
	v_cmp_gt_i32_e64 s[30:31], 0, v5
	v_or_b32_e32 v5, 34, v126
	v_sub_u32_e32 v5, v102, v5
	v_cvt_f32_u32_e32 v137, v7
	v_sub_u32_e32 v7, 0, v5
	v_max_i32_e32 v7, v5, v7
	v_cmp_gt_i32_e64 s[34:35], 0, v5
	v_or_b32_e32 v5, 35, v126
	v_sub_u32_e32 v5, v102, v5
	v_cvt_f32_u32_e32 v138, v7
	v_sub_u32_e32 v7, 0, v5
	v_max_i32_e32 v7, v5, v7
	v_cmp_gt_i32_e64 s[38:39], 0, v5
	v_or_b32_e32 v5, 48, v126
	v_sub_u32_e32 v5, v102, v5
	v_cvt_f32_u32_e32 v139, v7
	v_sub_u32_e32 v7, 0, v5
	v_max_i32_e32 v7, v5, v7
	v_cmp_gt_i32_e64 s[74:75], 0, v5
	v_or_b32_e32 v5, 49, v126
	v_sub_u32_e32 v5, v102, v5
	v_cvt_f32_u32_e32 v140, v7
	v_sub_u32_e32 v7, 0, v5
	v_max_i32_e32 v7, v5, v7
	v_cmp_gt_i32_e64 s[76:77], 0, v5
	v_or_b32_e32 v5, 50, v126
	v_sub_u32_e32 v5, v102, v5
	v_cvt_f32_u32_e32 v141, v7
	v_sub_u32_e32 v7, 0, v5
	v_max_i32_e32 v7, v5, v7
	v_cmp_gt_i32_e64 s[56:57], 0, v5
	v_or_b32_e32 v5, 51, v126
	v_sub_u32_e32 v5, v102, v5
	v_cvt_f32_u32_e32 v142, v7
	v_sub_u32_e32 v7, 0, v5
	v_max_i32_e32 v7, v5, v7
	v_cmp_gt_i32_e64 s[58:59], 0, v5
	v_or_b32_e32 v5, 64, v126
	v_sub_u32_e32 v5, v102, v5
	v_cvt_f32_u32_e32 v143, v7
	v_sub_u32_e32 v7, 0, v5
	v_max_i32_e32 v7, v5, v7
; #define LAS __attribute__((address_space(3)))
; __device__ __forceinline__ unsigned pk2(float lo, float hi) { return pg8::cvt_pk_bf16(lo, hi); }
; __device__ __forceinline__ float fexp2(float x) { return __builtin_amdgcn_exp2f(x); }
; __device__ __forceinline__ void ret_unit(LAS unsigned char* lds, int u, const bf16* PROJ, const int* pos, const float* dec_f, const float* dec_b, const bf16* ST,
;                                          const float* gn_w, const float* gn_b, bf16* MIX, int tid, const WsRef& wsr) {
;     ...
; #pragma unroll
;     for (int n = 0; n < 8; ++n) {
; #pragma unroll
;         for (int r = 0; r < 4; ++r) { const int key = n * 16 + 4 * fq + r; const int df = q - key; const float f = df >= 0 ? fexp2(lgf2 * (float)df) : fexp2(lgb2 * (float)(-df)); s[n][r] *= f; } }
; #pragma unroll
;     for (int kk = 0; kk < 4; ++kk) { u32x4 w; w.x = pk2(s[2 * kk][0], s[2 * kk][1]); w.y = pk2(s[2 * kk][2], s[2 * kk][3]); w.z = pk2(s[2 * kk + 1][0], s[2 * kk + 1][1]); w.w = pk2(s[2 * kk + 1][2], s[2 * kk + 1][3]);
;         pf[kk] = __builtin_bit_cast(bf16x8, w); }
;     f32x4 o[8];
; #pragma unroll
;     for (int n = 0; n < 8; ++n) o[n] = (f32x4){0.f, 0.f, 0.f, 0.f};
; #pragma unroll
;     for (int kk = 0; kk < 4; ++kk)
; #pragma unroll
;         for (int n = 0; n < 8; ++n) { const int sw = (2 * n + (fr >> 3)) & 7, jc = kk * 4 + (fq >> 1); const LAS bf16* vr = VT + (n * 16 + fr) * LDT + 4 * (fq & 1);
;             const u32x2 lo = *(const LAS u32x2*)(vr + ((jc ^ sw) << 3)), hi = *(const LAS u32x2*)(vr + (((jc + 2) ^ sw) << 3)); u32x4 w; w.x = lo.x; w.y = lo.y; w.z = hi.x; w.w = hi.y;
	v_cmp_gt_i32_e64 s[60:61], 0, v5
	v_or_b32_e32 v5, 0x41, v126
	v_sub_u32_e32 v5, v102, v5
	v_cvt_f32_u32_e32 v144, v7
	v_sub_u32_e32 v7, 0, v5
	v_max_i32_e32 v7, v5, v7
	v_cmp_gt_i32_e64 s[62:63], 0, v5
	v_or_b32_e32 v5, 0x42, v126
	v_sub_u32_e32 v5, v102, v5
	v_cvt_f32_u32_e32 v145, v7
	v_sub_u32_e32 v7, 0, v5
	v_max_i32_e32 v7, v5, v7
	v_cmp_gt_i32_e64 s[64:65], 0, v5
	v_or_b32_e32 v5, 0x43, v126
	v_sub_u32_e32 v5, v102, v5
	v_cvt_f32_u32_e32 v146, v7
	v_sub_u32_e32 v7, 0, v5
	v_max_i32_e32 v7, v5, v7
	v_cmp_gt_i32_e64 s[14:15], 0, v5
	v_or_b32_e32 v5, 0x50, v126
	v_sub_u32_e32 v5, v102, v5
	v_cvt_f32_u32_e32 v147, v7
	v_sub_u32_e32 v7, 0, v5
	v_max_i32_e32 v7, v5, v7
	v_cmp_gt_i32_e64 s[16:17], 0, v5
	v_or_b32_e32 v5, 0x51, v126
	v_sub_u32_e32 v5, v102, v5
	v_cvt_f32_u32_e32 v148, v7
	v_sub_u32_e32 v7, 0, v5
	v_max_i32_e32 v7, v5, v7
	v_cmp_gt_i32_e64 s[24:25], 0, v5
	v_or_b32_e32 v5, 0x52, v126
	v_sub_u32_e32 v5, v102, v5
	v_cvt_f32_u32_e32 v149, v7
	v_sub_u32_e32 v7, 0, v5
	v_max_i32_e32 v7, v5, v7
	v_cmp_gt_i32_e64 s[78:79], 0, v5
	v_or_b32_e32 v5, 0x53, v126
	v_sub_u32_e32 v5, v102, v5
	v_cvt_f32_u32_e32 v150, v7
	v_sub_u32_e32 v7, 0, v5
	s_mov_b32 s73, s2
	v_max_i32_e32 v7, v5, v7
	v_cmp_gt_i32_e64 s[2:3], 0, v5
	v_or_b32_e32 v5, 0x60, v126
	v_sub_u32_e32 v5, v102, v5
	v_cvt_f32_u32_e32 v151, v7
	v_sub_u32_e32 v7, 0, v5
	v_max_i32_e32 v7, v5, v7
	v_cmp_gt_i32_e64 s[92:93], 0, v5
	v_or_b32_e32 v5, 0x61, v126
	v_sub_u32_e32 v5, v102, v5
	v_cvt_f32_u32_e32 v152, v7
	v_sub_u32_e32 v7, 0, v5
	v_max_i32_e32 v7, v5, v7
	v_cmp_gt_i32_e32 vcc, 0, v5
	v_or_b32_e32 v5, 0x62, v126
	v_sub_u32_e32 v5, v102, v5
	v_cvt_f32_u32_e32 v153, v7
	v_sub_u32_e32 v7, 0, v5
	v_max_i32_e32 v7, v5, v7
	v_cmp_gt_i32_e64 s[94:95], 0, v5
	v_or_b32_e32 v5, 0x63, v126
	v_sub_u32_e32 v5, v102, v5
	v_cvt_f32_u32_e32 v154, v7
	v_sub_u32_e32 v7, 0, v5
	v_max_i32_e32 v7, v5, v7
	v_cmp_gt_i32_e64 s[8:9], 0, v5
	v_or_b32_e32 v5, 0x70, v126
	v_sub_u32_e32 v5, v102, v5
	v_writelane_b32 v255, s8, 4
	v_cvt_f32_u32_e32 v155, v7
	v_sub_u32_e32 v7, 0, v5
	v_writelane_b32 v255, s9, 5
	v_max_i32_e32 v7, v5, v7
	v_cmp_gt_i32_e64 s[8:9], 0, v5
	v_or_b32_e32 v5, 0x71, v126
	v_sub_u32_e32 v5, v102, v5
	v_writelane_b32 v255, s8, 50
	v_cvt_f32_u32_e32 v156, v7
	v_sub_u32_e32 v7, 0, v5
	v_writelane_b32 v255, s9, 51
	v_max_i32_e32 v7, v5, v7
	v_cmp_gt_i32_e64 s[8:9], 0, v5
	v_or_b32_e32 v5, 0x72, v126
	v_sub_u32_e32 v5, v102, v5
	v_writelane_b32 v255, s8, 52
	v_cvt_f32_u32_e32 v157, v7
	v_sub_u32_e32 v7, 0, v5
	v_writelane_b32 v255, s9, 53
	v_max_i32_e32 v7, v5, v7
	v_cmp_gt_i32_e64 s[8:9], 0, v5
	v_or_b32_e32 v5, 0x73, v126
	v_sub_u32_e32 v5, v102, v5
	v_cvt_f32_u32_e32 v158, v7
	v_sub_u32_e32 v7, 0, v5
	v_lshrrev_b32_e32 v99, 4, v128
	v_writelane_b32 v255, s8, 54
	v_max_i32_e32 v7, v5, v7
	v_lshrrev_b32_e32 v8, 1, v128
	v_writelane_b32 v255, s9, 55
	v_cmp_gt_i32_e64 s[8:9], 0, v5
	v_cvt_f32_u32_e32 v159, v7
	v_bfe_u32 v5, v128, 3, 1
	v_bfe_u32 v7, v99, 1, 1
	v_and_b32_e32 v8, 8, v8
	v_add_u32_e32 v8, s0, v8
	v_xor_b32_e32 v9, v7, v5
	v_mad_u32_u24 v160, v3, s1, v8
	v_lshlrev_b32_e32 v161, 4, v9
	v_bitop3_b32 v9, v7, v5, 2 bitop3:0x36
	v_add_u32_e32 v173, v8, v125
	v_bitop3_b32 v8, v7, v5, 4 bitop3:0x36
	v_lshlrev_b32_e32 v162, 4, v9
	v_or_b32_e32 v9, 2, v5
	v_bitop3_b32 v10, v5, v7, 2 bitop3:0x36
	v_lshlrev_b32_e32 v176, 4, v8
	v_bitop3_b32 v8, v7, v5, 6 bitop3:0x36
	v_lshlrev_b32_e32 v164, 4, v10
	v_bitop3_b32 v10, v7, v5, 2 bitop3:0x14
	v_lshlrev_b32_e32 v177, 4, v8
	v_bitop3_b32 v8, v7, v9, 4 bitop3:0x36
	v_lshlrev_b32_e32 v165, 4, v10
	v_or_b32_e32 v10, 4, v5
	v_bitop3_b32 v11, v5, v7, 4 bitop3:0x36
	v_lshlrev_b32_e32 v178, 4, v8
	v_bitop3_b32 v8, v7, v9, 6 bitop3:0x36
	v_lshlrev_b32_e32 v167, 4, v11
	v_bitop3_b32 v11, v7, v10, 2 bitop3:0x36
	v_lshlrev_b32_e32 v179, 4, v8
	v_bitop3_b32 v8, v7, v5, 4 bitop3:0x14
	v_lshlrev_b32_e32 v168, 4, v11
	v_or_b32_e32 v11, 6, v5
	v_lshlrev_b32_e32 v180, 4, v8
	v_bitop3_b32 v8, v7, v10, 6 bitop3:0x36
	v_lshlrev_b32_e32 v181, 4, v8
	v_bitop3_b32 v8, v7, v11, 4 bitop3:0x36
	v_lshlrev_b32_e32 v182, 4, v8
	v_bitop3_b32 v8, v7, v5, 6 bitop3:0x14
	v_lshlrev_b32_e32 v183, 4, v8
	v_bitop3_b32 v8, v7, v5, 8 bitop3:0x36
	v_lshlrev_b32_e32 v184, 4, v8
	v_bitop3_b32 v8, v7, v5, 10 bitop3:0x36
	v_lshlrev_b32_e32 v185, 4, v8
	v_bitop3_b32 v8, v7, v9, 8 bitop3:0x36
	v_lshlrev_b32_e32 v186, 4, v8
	v_bitop3_b32 v8, v7, v9, 10 bitop3:0x36
	v_lshlrev_b32_e32 v187, 4, v8
	v_bitop3_b32 v8, v7, v10, 8 bitop3:0x36
	v_lshlrev_b32_e32 v188, 4, v8
	v_bitop3_b32 v8, v7, v10, 10 bitop3:0x36
	v_lshlrev_b32_e32 v189, 4, v8
	v_bitop3_b32 v8, v7, v11, 8 bitop3:0x36
	v_lshlrev_b32_e32 v190, 4, v8
	v_bitop3_b32 v8, v7, v11, 10 bitop3:0x36
	v_bitop3_b32 v12, v5, v7, 6 bitop3:0x36
	v_lshlrev_b32_e32 v191, 4, v8
	v_bitop3_b32 v8, v7, v5, 12 bitop3:0x36
	v_bitop3_b32 v5, v7, v5, 14 bitop3:0x36
	v_lshlrev_b32_e32 v193, 4, v5
	v_bitop3_b32 v5, v7, v9, 12 bitop3:0x36
	v_lshlrev_b32_e32 v194, 4, v5
	v_bitop3_b32 v5, v7, v9, 14 bitop3:0x36
	v_lshlrev_b32_e32 v195, 4, v5
	v_bitop3_b32 v5, v7, v10, 12 bitop3:0x36
	v_lshlrev_b32_e32 v196, 4, v5
	v_bitop3_b32 v5, v7, v10, 14 bitop3:0x36
	v_lshlrev_b32_e32 v197, 4, v5
	v_bitop3_b32 v5, v7, v11, 12 bitop3:0x36
	v_lshlrev_b32_e32 v198, 4, v5
	v_bitop3_b32 v5, v7, v11, 14 bitop3:0x36
	v_lshlrev_b32_e32 v192, 4, v8
	v_lshlrev_b32_e32 v199, 4, v5
	v_lshlrev_b32_e32 v5, 1, v4
	v_mul_u32_u24_e32 v8, 0x88, v99
	v_lshlrev_b32_e32 v170, 4, v12
	v_bitop3_b32 v12, v7, v11, 2 bitop3:0x36
	v_add_u32_e32 v7, 0, v5
	v_add_u32_e32 v5, s0, v5
	v_lshlrev_b32_e32 v8, 1, v8
	v_mul_u32_u24_e32 v6, 0x110, v3
	v_add_u32_e32 v200, v7, v8
	v_add_u32_e32 v201, v5, v8
; #define LAS __attribute__((address_space(3)))
; __device__ __forceinline__ u32x4 ws_load16(const WsRef& w, unsigned byte_off) { return __builtin_bit_cast(u32x4, __builtin_amdgcn_raw_buffer_load_b128(w.r, byte_off, 0, 0)); }
; __device__ __forceinline__ float log_sigmoid(float x) { return -log1pf(expf(-x)); }
; __device__ __forceinline__ void ret_unit(LAS unsigned char* lds, int u, const bf16* PROJ, const int* pos, const float* dec_f, const float* dec_b, const bf16* ST,
;                                          const float* gn_w, const float* gn_b, bf16* MIX, int tid, const WsRef& wsr) {
;     const int lane = tid & 63, wave = tid >> 6, fr = lane & 15, fq = lane >> 4;
;     const int bh = u >> 6, c = u & 63, b = bh >> 2, h = bh & 3;
;     const size_t row0 = (size_t)b * SEQ + (size_t)c * 128;
;     LAS bf16* Qs = (LAS bf16*)lds; LAS bf16* Ks = (LAS bf16*)(lds + TILE_B); LAS bf16* VT = (LAS bf16*)(lds + 2 * TILE_B);
;     const float lgf2 = log_sigmoid(dec_f[h]) * LOG2E, lgb2 = log_sigmoid(dec_b[h]) * LOG2E;
;     const u32x4* sfp = (const u32x4*)(ST + ((size_t)bh * 64 + c) * 16384); const u32x4* sbp = (const u32x4*)(ST + ((size_t)(8 + bh) * 64 + c) * 16384);
;     u32x4 sf[4], sb[4];
; #pragma unroll
;     for (int i = 0; i < 4; ++i) { sf[i] = sfp[tid + 512 * i]; sb[i] = sbp[tid + 512 * i]; }
;     u32x4 rq1[2], rq2[2], rk1[2], rk2[2], rv[4]; float rp[2];
; #pragma unroll
;     for (int ii = 0; ii < 2; ++ii) { const int it = tid + 512 * ii, dc = it & 7, j = it >> 3; const unsigned qo = (unsigned)WS_PROJ + (unsigned)(((unsigned)(row0 + j) * INC + h * 128 + dc * 8) * 2u);
;         rq1[ii] = ws_load16(wsr, qo); rq2[ii] = ws_load16(wsr, qo + 128u); rk1[ii] = ws_load16(wsr, qo + 1024u); rk2[ii] = ws_load16(wsr, qo + 1152u); rp[ii] = (float)pos[row0 + j]; }
	v_mul_u32_u24_e32 v8, 0x88, v117
	v_mul_u32_u24_e32 v3, 0x88, v3
	v_lshrrev_b32_e32 v118, 4, v0
	v_add_u32_e32 v124, 0, v2
	v_lshlrev_b32_e32 v8, 1, v8
	v_lshlrev_b32_e32 v3, 1, v3
	v_add_u32_e32 v202, v7, v8
	v_add_u32_e32 v203, v5, v8
	v_mul_u32_u24_e32 v8, 0x88, v118
	v_add_u32_e32 v209, v124, v3
	v_add3_u32 v210, s0, v2, v3
	v_add_u32_e32 v3, 1, v102
	v_lshlrev_b32_e32 v8, 1, v8
	v_cvt_f32_u32_e32 v218, v3
	v_sub_u32_e32 v3, 0x80, v102
	v_add_u32_e32 v205, v7, v8
	v_add_u32_e32 v206, v5, v8
	v_mul_u32_u24_e32 v8, 0x88, v119
	v_cvt_f32_i32_e32 v219, v3
	v_mbcnt_lo_u32_b32 v3, -1, 0
	v_lshlrev_b32_e32 v8, 1, v8
	v_mbcnt_hi_u32_b32 v3, -1, v3
	v_writelane_b32 v255, s8, 56
	v_add_u32_e32 v207, v7, v8
	v_and_b32_e32 v7, 64, v3
	v_writelane_b32 v255, s9, 57
	v_add_u32_e32 v208, v5, v8
	v_xor_b32_e32 v5, 16, v3
	v_add_u32_e32 v7, 64, v7
	v_cmp_lt_i32_e64 s[68:69], v5, v7
	v_writelane_b32 v255, s73, 58
	v_mov_b32_e32 v97, 0
	v_cndmask_b32_e64 v5, v3, v5, s[68:69]
	v_readlane_b32 s40, v255, 10
	v_lshlrev_b32_e32 v220, 2, v5
	v_xor_b32_e32 v5, 32, v3
	v_readlane_b32 s41, v255, 11
	v_cmp_lt_i32_e64 s[68:69], v5, v7
	v_readlane_b32 s42, v255, 12
	v_readlane_b32 s43, v255, 13
	v_readlane_b32 s44, v255, 14
	v_readlane_b32 s45, v255, 15
	v_readlane_b32 s46, v255, 16
	v_readlane_b32 s47, v255, 17
	v_readlane_b32 s40, v255, 8
	v_mad_u32_u24 v1, v102, s1, 0
	v_cndmask_b32_e64 v3, v3, v5, s[68:69]
	v_readlane_b32 s48, v255, 18
	v_readlane_b32 s49, v255, 19
	v_readlane_b32 s50, v255, 20
	v_readlane_b32 s51, v255, 21
	v_readlane_b32 s52, v255, 22
	v_readlane_b32 s53, v255, 23
	v_readlane_b32 s46, v255, 48
	v_readlane_b32 s44, v255, 46
	v_readlane_b32 s42, v255, 44
	v_readlane_b32 s41, v255, 9
	v_mov_b32_e32 v101, v97
	v_add_u32_e32 v163, 0x1100, v160
	v_add_u32_e32 v166, 0x2200, v160
	v_add_u32_e32 v169, 0x3300, v160
	v_lshlrev_b32_e32 v171, 4, v12
	v_add_u32_e32 v172, 0x4400, v160
	v_add_u32_e32 v174, 0x1100, v173
	v_add_u32_e32 v175, 0x2200, v173
	v_add_u32_e32 v211, 0x1100, v210
	v_add_u32_e32 v212, 0x2200, v210
	v_add_u32_e32 v213, 0x3300, v210
	v_add_u32_e32 v214, 0x4400, v210
	v_add_u32_e32 v215, 0x5500, v210
	v_add_u32_e32 v216, 0x6600, v210
	v_add_u32_e32 v217, 0x7700, v210
	v_mov_b32_e32 v103, v97
	v_lshlrev_b32_e32 v221, 2, v3
	v_or_b32_e32 v222, 0x400, v4
	v_mov_b32_e32 v223, 0x3ecc95a3
	v_lshlrev_b32_e32 v96, 4, v128
	v_lshlrev_b32_e32 v224, 4, v0
	s_movk_i32 s9, 0xc00
	s_mov_b32 s10, 0x3db504f3
	v_add_u32_e32 v225, v1, v2
	v_add_u32_e32 v226, v124, v6
	v_mov_b32_e32 v227, 0x358637bd
	s_movk_i32 s72, 0x1800
	v_mov_b32_e32 v228, 0x7f800000
	v_mov_b32_e32 v104, 0x3f317218
	v_mov_b32_e32 v229, 0x8800000
	v_readlane_b32 s54, v255, 24
	v_readlane_b32 s55, v255, 25
	s_mov_b64 s[50:51], s[80:81]
	s_mov_b64 s[48:49], s[82:83]
	v_readlane_b32 s47, v255, 49
	v_readlane_b32 s45, v255, 47
	v_readlane_b32 s43, v255, 45
	s_mov_b64 s[52:53], s[4:5]
	s_mov_b32 s41, 0xbfb8aa3b
	s_mov_b32 s33, 0x3f317218
	s_mov_b32 s100, 0
.LBB0_438:
	s_ashr_i32 s0, s73, 6
	s_and_b32 s80, s0, 3
	s_lshl_b32 s1, s80, 2
	v_mov_b32_e32 v86, s1
	global_load_dword v68, v86, s[18:19]
	global_load_dword v87, v86, s[20:21]
	s_and_b32 s82, s73, 63
	s_ashr_i32 s4, s73, 8
	s_ashr_i32 s5, s4, 31
	s_lshl_b32 s81, s82, 7
	s_ashr_i32 s1, s0, 31
	s_lshl_b64 s[0:1], s[0:1], 21
	s_add_u32 s0, s54, s0
	s_addc_u32 s1, s55, s1
	s_mov_b32 s88, s84
	s_movk_i32 s8, 0x2000
	s_lshl_b32 s68, s82, 15
	s_add_u32 s0, s0, s68
	s_addc_u32 s1, s1, 0
	s_add_u32 s82, s0, 0x1000000
	v_lshl_add_u64 v[2:3], s[0:1], 0, v[96:97]
	s_addc_u32 s83, s1, 0
	v_add_co_u32_e64 v8, s[68:69], s8, v2
	v_lshl_add_u64 v[28:29], s[82:83], 0, v[96:97]
	s_nop 0
	v_addc_co_u32_e64 v9, s[68:69], 0, v3, s[68:69]
	v_add_co_u32_e64 v16, s[68:69], s8, v28
	global_load_dwordx4 v[4:7], v96, s[0:1]
	global_load_dwordx4 v[12:15], v96, s[82:83]
	v_addc_co_u32_e64 v17, s[68:69], 0, v29, s[68:69]
	global_load_dwordx4 v[8:11], v[8:9], off
	s_nop 0
	global_load_dwordx4 v[16:19], v[16:17], off
	s_nop 0
	global_load_dwordx4 v[24:27], v224, s[0:1]
	global_load_dwordx4 v[20:23], v224, s[82:83]
	s_movk_i32 s0, 0x6000
	v_add_co_u32_e64 v2, s[68:69], s0, v2
	s_lshl_b64 s[4:5], s[4:5], 13
	s_nop 0
	v_addc_co_u32_e64 v3, s[68:69], 0, v3, s[68:69]
	global_load_dwordx4 v[32:35], v[2:3], off
	v_add_co_u32_e64 v2, s[68:69], s0, v28
	s_or_b32 s4, s4, s81
	s_nop 0
	v_addc_co_u32_e64 v3, s[68:69], 0, v29, s[68:69]
	s_lshl_b32 s0, s80, 7
	v_or_b32_e32 v0, s4, v98
	global_load_dwordx4 v[36:39], v[2:3], off
	v_or_b32_e32 v2, s0, v106
	v_mul_lo_u32 v3, v0, s9
	v_mov_b32_e32 v1, s5
	v_or_b32_e32 v3, v3, v2
	v_lshl_add_u32 v3, v3, 1, v229
	v_lshl_add_u64 v[0:1], v[0:1], 2, s[12:13]
	buffer_load_dwordx4 v[50:53], v3, s[88:91], 0 offen
	buffer_load_dwordx4 v[54:57], v3, s[88:91], 0 offen offset:128
	buffer_load_dwordx4 v[58:61], v3, s[88:91], 0 offen offset:1024
	buffer_load_dwordx4 v[62:65], v3, s[88:91], 0 offen offset:1152
	v_lshl_add_u64 v[66:67], s[4:5], 0, v[100:101]
	global_load_dword v0, v[0:1], off
	s_waitcnt vmcnt(13)
	s_add_i32 s101, s80, 1
	s_cmp_eq_u32 s100, s101
	s_cbranch_scc0 .Lp4_log
	v_mov_b32_e32 v48, s98
	v_mov_b32_e32 v105, s99
	s_branch .Lp4_logdone
; __device__ __forceinline__ float log_sigmoid(float x) { return -log1pf(expf(-x)); }
; __device__ __forceinline__ void ret_unit(LAS unsigned char* lds, int u, const bf16* PROJ, const int* pos, const float* dec_f, const float* dec_b, const bf16* ST,
;                                          const float* gn_w, const float* gn_b, bf16* MIX, int tid, const WsRef& wsr) {
;     ...
;     const float lgf2 = log_sigmoid(dec_f[h]) * LOG2E, lgb2 = log_sigmoid(dec_b[h]) * LOG2E;
.Lp4_log:
	s_mov_b32 s1, 0x42ce8ed0
	s_mov_b32 s83, 0xc2b17218
	s_mov_b32 s11, 0x3f2aaaab
	s_mov_b32 s88, 0x7f800000
	s_mov_b32 s8, 0x33800000
	v_mul_f32_e32 v69, 0xbfb8aa3b, v68
	v_fma_f32 v70, v68, s41, -v69
	v_rndne_f32_e32 v71, v69
	v_fmac_f32_e32 v70, 0xb2a5705f, v68
	v_sub_f32_e32 v69, v69, v71
	v_add_f32_e32 v69, v69, v70
	v_exp_f32_e32 v69, v69
	v_cvt_i32_f32_e32 v70, v71
	v_cmp_nlt_f32_e64 s[68:69], s1, v68
	v_ldexp_f32 v69, v69, v70
	s_nop 0
	v_cndmask_b32_e64 v69, 0, v69, s[68:69]
	v_cmp_ngt_f32_e64 s[68:69], s83, v68
	s_nop 1
	v_cndmask_b32_e64 v85, v228, v69, s[68:69]
	v_add_f32_e32 v70, 1.0, v85
	v_add_f32_e32 v68, -1.0, v70
	v_sub_f32_e32 v69, v68, v70
	v_add_f32_e32 v69, 1.0, v69
	v_sub_f32_e32 v68, v85, v68
	v_add_f32_e32 v71, v68, v69
	v_frexp_mant_f32_e32 v68, v70
	v_cmp_gt_f32_e64 s[68:69], s11, v68
	v_cvt_f64_f32_e32 v[68:69], v70
	v_frexp_exp_i32_f64_e32 v68, v[68:69]
	v_subbrev_co_u32_e64 v76, s[68:69], 0, v68, s[68:69]
	v_sub_u32_e32 v68, 0, v76
	v_ldexp_f32 v69, v70, v68
	v_add_f32_e32 v70, -1.0, v69
	v_add_f32_e32 v72, 1.0, v69
	v_ldexp_f32 v68, v71, v68
	v_add_f32_e32 v71, 1.0, v70
	v_add_f32_e32 v73, -1.0, v72
	v_sub_f32_e32 v71, v69, v71
	v_sub_f32_e32 v69, v69, v73
	v_add_f32_e32 v71, v68, v71
	v_add_f32_e32 v68, v68, v69
	v_add_f32_e32 v77, v72, v68
	v_rcp_f32_e32 v79, v77
	v_sub_f32_e32 v69, v72, v77
	v_add_f32_e32 v78, v68, v69
	v_add_f32_e32 v69, v70, v71
	v_mul_f32_e32 v81, v69, v79
	v_sub_f32_e32 v68, v70, v69
	v_mul_f32_e32 v70, v77, v81
	v_fma_f32 v72, v81, v77, -v70
	v_fmac_f32_e32 v72, v81, v78
	v_add_f32_e32 v80, v71, v68
	v_add_f32_e32 v68, v70, v72
	v_sub_f32_e32 v71, v69, v68
	v_pk_add_f32 v[74:75], v[68:69], v[70:71] neg_lo:[0,1] neg_hi:[0,1]
	v_mov_b32_e32 v73, v68
	v_pk_add_f32 v[68:69], v[74:75], v[72:73] neg_lo:[0,1] neg_hi:[0,1]
	v_cmp_neq_f32_e64 s[68:69], s88, v85
	v_add_f32_e32 v69, v80, v69
	v_add_f32_e32 v68, v68, v69
	v_add_f32_e32 v69, v71, v68
	v_mul_f32_e32 v80, v79, v69
	v_mul_f32_e32 v70, v77, v80
	v_fma_f32 v72, v80, v77, -v70
	v_fmac_f32_e32 v72, v80, v78
	v_sub_f32_e32 v71, v71, v69
	v_add_f32_e32 v77, v68, v71
	v_add_f32_e32 v68, v70, v72
	v_sub_f32_e32 v71, v69, v68
	v_pk_add_f32 v[74:75], v[68:69], v[70:71] neg_lo:[0,1] neg_hi:[0,1]
	v_mov_b32_e32 v73, v68
	v_pk_add_f32 v[68:69], v[74:75], v[72:73] neg_lo:[0,1] neg_hi:[0,1]
	s_nop 0
	v_add_f32_e32 v69, v77, v69
	v_add_f32_e32 v68, v68, v69
	v_add_f32_e32 v69, v81, v80
	v_add_f32_e32 v68, v71, v68
	v_sub_f32_e32 v70, v69, v81
	v_mul_f32_e32 v68, v79, v68
	v_sub_f32_e32 v70, v80, v70
	v_add_f32_e32 v70, v70, v68
	v_add_f32_e32 v72, v69, v70
	v_mul_f32_e32 v73, v72, v72
	v_fmamk_f32 v68, v73, 0x3e9b6dac, v223
	v_fmaak_f32 v105, v73, v68, 0x3f2aaada
	v_cvt_f32_i32_e32 v68, v76
	v_sub_f32_e32 v69, v72, v69
	v_sub_f32_e32 v69, v70, v69
	v_ldexp_f32 v74, v69, 1
	v_mul_f32_e32 v69, v72, v73
	v_ldexp_f32 v71, v72, 1
	v_pk_mul_f32 v[72:73], v[68:69], v[104:105]
	s_nop 0
	v_fma_f32 v70, v68, s33, -v72
	v_fmac_f32_e32 v70, 0xb102e308, v68
	v_pk_add_f32 v[68:69], v[72:73], v[70:71]
	s_nop 0
	v_sub_f32_e32 v71, v69, v71
	v_sub_f32_e32 v71, v73, v71
	v_add_f32_e32 v75, v74, v71
	v_mov_b32_e32 v74, v72
	v_pk_add_f32 v[72:73], v[68:69], v[72:73] neg_lo:[0,1] neg_hi:[0,1]
	v_pk_add_f32 v[76:77], v[68:69], v[74:75]
	v_mov_b32_e32 v71, v68
	v_mov_b32_e32 v73, v77
	v_pk_add_f32 v[78:79], v[70:71], v[72:73] neg_lo:[0,1] neg_hi:[0,1]
	v_pk_add_f32 v[70:71], v[70:71], v[72:73]
	v_mov_b32_e32 v82, v69
	v_pk_add_f32 v[72:73], v[70:71], v[68:69] op_sel:[1,0] op_sel_hi:[0,1] neg_lo:[0,1] neg_hi:[0,1]
	v_pk_add_f32 v[80:81], v[76:77], v[72:73] op_sel_hi:[1,0] neg_lo:[0,1] neg_hi:[0,1]
	v_mov_b32_e32 v76, v77
	v_mov_b32_e32 v77, v71
	v_mov_b32_e32 v83, v72
	v_pk_add_f32 v[72:73], v[76:77], v[82:83] neg_lo:[0,1] neg_hi:[0,1]
	v_mov_b32_e32 v74, v75
	v_mov_b32_e32 v75, v68
	v_pk_add_f32 v[68:69], v[74:75], v[72:73] neg_lo:[0,1] neg_hi:[0,1]
	v_mov_b32_e32 v80, v78
	v_pk_add_f32 v[72:73], v[80:81], v[68:69]
	v_mov_b32_e32 v79, v71
	v_pk_add_f32 v[74:75], v[72:73], v[72:73] op_sel:[0,1] op_sel_hi:[1,0]
	s_nop 0
	v_pk_add_f32 v[70:71], v[70:71], v[74:75] op_sel:[1,0] op_sel_hi:[0,1]
	v_mov_b32_e32 v73, v70
	v_pk_add_f32 v[76:77], v[72:73], v[78:79] neg_lo:[0,1] neg_hi:[0,1]
	v_mov_b32_e32 v69, v74
	v_sub_f32_e32 v71, v72, v76
	v_pk_add_f32 v[68:69], v[68:69], v[76:77] neg_lo:[0,1] neg_hi:[0,1]
	v_sub_f32_e32 v71, v78, v71
	v_add_f32_e32 v68, v68, v71
	v_add_f32_e32 v68, v68, v69
	v_mov_b32_e32 v69, v87
	v_add_f32_e32 v68, v70, v68
	v_cndmask_b32_e64 v68, v228, v68, s[68:69]
	v_cmp_lt_f32_e64 s[68:69], |v85|, s8
	v_mul_f32_e32 v70, 0xbfb8aa3b, v69
	v_fma_f32 v71, v69, s41, -v70
	v_rndne_f32_e32 v72, v70
	v_fmac_f32_e32 v71, 0xb2a5705f, v69
	v_sub_f32_e32 v70, v70, v72
	v_add_f32_e32 v70, v70, v71
	v_exp_f32_e32 v70, v70
	v_cvt_i32_f32_e32 v71, v72
	v_cndmask_b32_e64 v68, v68, v85, s[68:69]
	v_cmp_nlt_f32_e64 s[68:69], s1, v69
	v_ldexp_f32 v70, v70, v71
	v_cndmask_b32_e64 v70, 0, v70, s[68:69]
	v_cmp_ngt_f32_e64 s[68:69], s83, v69
	v_cndmask_b32_e64 v69, v228, v70, s[68:69]
	v_add_f32_e32 v72, 1.0, v69
	v_add_f32_e32 v70, -1.0, v72
	v_sub_f32_e32 v71, v70, v72
	v_add_f32_e32 v71, 1.0, v71
	v_sub_f32_e32 v70, v69, v70
	v_add_f32_e32 v73, v70, v71
	v_frexp_mant_f32_e32 v70, v72
	v_cmp_gt_f32_e64 s[68:69], s11, v70
	v_cvt_f64_f32_e32 v[70:71], v72
	v_frexp_exp_i32_f64_e32 v70, v[70:71]
	v_subbrev_co_u32_e64 v78, s[68:69], 0, v70, s[68:69]
	v_sub_u32_e32 v70, 0, v78
	v_ldexp_f32 v71, v72, v70
	v_add_f32_e32 v72, -1.0, v71
	v_add_f32_e32 v74, 1.0, v71
	v_ldexp_f32 v70, v73, v70
	v_add_f32_e32 v73, 1.0, v72
	v_add_f32_e32 v75, -1.0, v74
	v_sub_f32_e32 v73, v71, v73
; __device__ __forceinline__ float fexp2(float x) { return __builtin_amdgcn_exp2f(x); }
; __device__ __forceinline__ float log_sigmoid(float x) { return -log1pf(expf(-x)); }
; __device__ __forceinline__ void ret_unit(LAS unsigned char* lds, int u, const bf16* PROJ, const int* pos, const float* dec_f, const float* dec_b, const bf16* ST,
;                                          const float* gn_w, const float* gn_b, bf16* MIX, int tid, const WsRef& wsr) {
;     ...
;     const float lgf2 = log_sigmoid(dec_f[h]) * LOG2E, lgb2 = log_sigmoid(dec_b[h]) * LOG2E;
;     ...
; #pragma unroll
;     for (int n = 0; n < 8; ++n) {
; #pragma unroll
;         for (int r = 0; r < 4; ++r) { const int key = n * 16 + 4 * fq + r; const int df = q - key; const float f = df >= 0 ? fexp2(lgf2 * (float)df) : fexp2(lgb2 * (float)(-df)); s[n][r] *= f; } }
	v_sub_f32_e32 v71, v71, v75
	v_add_f32_e32 v73, v70, v73
	v_add_f32_e32 v70, v70, v71
	v_add_f32_e32 v79, v74, v70
	v_rcp_f32_e32 v81, v79
	v_sub_f32_e32 v71, v74, v79
	v_add_f32_e32 v80, v70, v71
	v_add_f32_e32 v71, v72, v73
	v_mul_f32_e32 v83, v71, v81
	v_sub_f32_e32 v70, v72, v71
	v_mul_f32_e32 v72, v79, v83
	v_fma_f32 v74, v83, v79, -v72
	v_fmac_f32_e32 v74, v83, v80
	v_add_f32_e32 v82, v73, v70
	v_add_f32_e32 v70, v72, v74
	v_sub_f32_e32 v73, v71, v70
	v_pk_add_f32 v[76:77], v[70:71], v[72:73] neg_lo:[0,1] neg_hi:[0,1]
	v_mov_b32_e32 v75, v70
	v_pk_add_f32 v[70:71], v[76:77], v[74:75] neg_lo:[0,1] neg_hi:[0,1]
	v_cmp_neq_f32_e64 s[68:69], s88, v69
	v_add_f32_e32 v71, v82, v71
	v_add_f32_e32 v70, v70, v71
	v_add_f32_e32 v71, v73, v70
	v_mul_f32_e32 v82, v81, v71
	v_mul_f32_e32 v72, v79, v82
	v_fma_f32 v74, v82, v79, -v72
	v_fmac_f32_e32 v74, v82, v80
	v_sub_f32_e32 v73, v73, v71
	v_add_f32_e32 v79, v70, v73
	v_add_f32_e32 v70, v72, v74
	v_sub_f32_e32 v73, v71, v70
	v_pk_add_f32 v[76:77], v[70:71], v[72:73] neg_lo:[0,1] neg_hi:[0,1]
	v_mov_b32_e32 v75, v70
	v_pk_add_f32 v[70:71], v[76:77], v[74:75] neg_lo:[0,1] neg_hi:[0,1]
	v_add_f32_e32 v71, v79, v71
	v_add_f32_e32 v70, v70, v71
	v_add_f32_e32 v71, v83, v82
	v_add_f32_e32 v70, v73, v70
	v_sub_f32_e32 v72, v71, v83
	v_mul_f32_e32 v70, v81, v70
	v_sub_f32_e32 v72, v82, v72
	v_add_f32_e32 v72, v72, v70
	v_add_f32_e32 v74, v71, v72
	v_mul_f32_e32 v75, v74, v74
	v_fmamk_f32 v70, v75, 0x3e9b6dac, v223
	v_fmaak_f32 v105, v75, v70, 0x3f2aaada
	v_cvt_f32_i32_e32 v70, v78
	v_sub_f32_e32 v71, v74, v71
	v_sub_f32_e32 v71, v72, v71
	v_ldexp_f32 v76, v71, 1
	v_mul_f32_e32 v71, v74, v75
	v_ldexp_f32 v73, v74, 1
	v_pk_mul_f32 v[74:75], v[70:71], v[104:105]
	v_mul_f32_e32 v105, 0xbfb8aa3b, v68
	v_fma_f32 v72, v70, s33, -v74
	v_fmac_f32_e32 v72, 0xb102e308, v70
	v_pk_add_f32 v[70:71], v[74:75], v[72:73]
	s_mov_b32 s88, s84
	v_sub_f32_e32 v73, v71, v73
	v_sub_f32_e32 v73, v75, v73
	v_add_f32_e32 v77, v76, v73
	v_mov_b32_e32 v76, v74
	v_pk_add_f32 v[74:75], v[70:71], v[74:75] neg_lo:[0,1] neg_hi:[0,1]
	v_pk_add_f32 v[78:79], v[70:71], v[76:77]
	v_mov_b32_e32 v73, v70
	v_mov_b32_e32 v75, v79
	v_pk_add_f32 v[80:81], v[72:73], v[74:75] neg_lo:[0,1] neg_hi:[0,1]
	v_pk_add_f32 v[72:73], v[72:73], v[74:75]
	v_mov_b32_e32 v84, v71
	v_pk_add_f32 v[74:75], v[72:73], v[70:71] op_sel:[1,0] op_sel_hi:[0,1] neg_lo:[0,1] neg_hi:[0,1]
	v_pk_add_f32 v[82:83], v[78:79], v[74:75] op_sel_hi:[1,0] neg_lo:[0,1] neg_hi:[0,1]
	v_mov_b32_e32 v78, v79
	v_mov_b32_e32 v79, v73
	v_mov_b32_e32 v85, v74
	v_pk_add_f32 v[74:75], v[78:79], v[84:85] neg_lo:[0,1] neg_hi:[0,1]
	v_mov_b32_e32 v76, v77
	v_mov_b32_e32 v77, v70
	v_pk_add_f32 v[70:71], v[76:77], v[74:75] neg_lo:[0,1] neg_hi:[0,1]
	v_mov_b32_e32 v82, v80
	v_pk_add_f32 v[74:75], v[82:83], v[70:71]
	v_mov_b32_e32 v81, v73
	v_pk_add_f32 v[76:77], v[74:75], v[74:75] op_sel:[0,1] op_sel_hi:[1,0]
	s_nop 0
	v_pk_add_f32 v[72:73], v[72:73], v[76:77] op_sel:[1,0] op_sel_hi:[0,1]
	v_mov_b32_e32 v75, v72
	v_pk_add_f32 v[78:79], v[74:75], v[80:81] neg_lo:[0,1] neg_hi:[0,1]
	v_mov_b32_e32 v71, v76
	v_sub_f32_e32 v73, v74, v78
	v_pk_add_f32 v[70:71], v[70:71], v[78:79] neg_lo:[0,1] neg_hi:[0,1]
	v_sub_f32_e32 v73, v80, v73
	v_add_f32_e32 v70, v70, v73
	v_add_f32_e32 v70, v70, v71
	v_add_f32_e32 v70, v72, v70
	v_cndmask_b32_e64 v70, v228, v70, s[68:69]
	v_cmp_lt_f32_e64 s[68:69], |v69|, s8
	s_movk_i32 s8, 0x2000
	s_nop 0
	v_cndmask_b32_e64 v48, v70, v69, s[68:69]
	v_readfirstlane_b32 s99, v105
	s_mov_b32 s100, s101
	s_nop 1
	v_readfirstlane_b32 s98, v48
.Lp4_logdone:
	v_mul_f32_e32 v230, 0xbfb8aa3b, v48
	v_cndmask_b32_e64 v89, v105, v230, s[30:31]
	v_cndmask_b32_e64 v94, v105, v230, s[56:57]
	v_cndmask_b32_e64 v95, v105, v230, s[58:59]
	v_mul_f32_e32 v89, v89, v137
	v_cndmask_b32_e64 v92, v105, v230, s[74:75]
	v_cndmask_b32_e64 v93, v105, v230, s[76:77]
	v_mul_f32_e32 v94, v94, v142
	v_mul_f32_e32 v95, v95, v143
	v_exp_f32_e32 v89, v89
	v_mul_f32_e32 v92, v92, v140
	v_mul_f32_e32 v93, v93, v141
	v_exp_f32_e32 v94, v94
	v_exp_f32_e32 v95, v95
	v_exp_f32_e32 v92, v92
	v_exp_f32_e32 v93, v93
	v_cndmask_b32_e64 v130, v105, v230, s[60:61]
	v_cndmask_b32_e64 v131, v105, v230, s[62:63]
	v_cndmask_b32_e64 v48, v105, v230, s[42:43]
	v_mul_f32_e32 v130, v130, v144
	v_mul_f32_e32 v131, v131, v145
	v_mul_f32_e32 v48, v48, v127
	v_exp_f32_e32 v130, v130
	v_exp_f32_e32 v131, v131
	v_exp_f32_e32 v48, v48
	v_cndmask_b32_e64 v90, v105, v230, s[34:35]
	v_cndmask_b32_e64 v91, v105, v230, s[38:39]
	v_mul_f32_e32 v90, v90, v138
	v_mul_f32_e32 v91, v91, v139
	v_exp_f32_e32 v90, v90
	v_exp_f32_e32 v91, v91
	v_cndmask_b32_e64 v238, v105, v230, s[94:95]
	v_mul_f32_e32 v238, v238, v154
	v_exp_f32_e32 v238, v238
	v_cndmask_b32_e64 v234, v105, v230, s[78:79]
	v_cndmask_b32_e64 v235, v105, v230, s[2:3]
	v_cndmask_b32_e64 v236, v105, v230, s[92:93]
	v_cndmask_b32_e32 v237, v105, v230, vcc
	v_mul_f32_e32 v234, v234, v150
	v_mul_f32_e32 v235, v235, v151
	v_mul_f32_e32 v236, v236, v152
	v_mul_f32_e32 v237, v237, v153
	v_exp_f32_e32 v234, v234
	v_exp_f32_e32 v235, v235
	v_exp_f32_e32 v236, v236
	v_exp_f32_e32 v237, v237
	v_cndmask_b32_e64 v132, v105, v230, s[64:65]
	v_cndmask_b32_e64 v133, v105, v230, s[14:15]
	v_cndmask_b32_e64 v232, v105, v230, s[16:17]
	v_cndmask_b32_e64 v233, v105, v230, s[24:25]
	v_mul_f32_e32 v132, v132, v146
	v_mul_f32_e32 v133, v133, v147
	v_mul_f32_e32 v232, v232, v148
	v_mul_f32_e32 v233, v233, v149
	v_exp_f32_e32 v132, v132
	v_exp_f32_e32 v133, v133
	v_exp_f32_e32 v232, v232
	v_exp_f32_e32 v233, v233
	s_mov_b32 s1, 0x800000
	s_add_i32 s73, s73, s40
	s_cmpk_lt_i32 s73, 0x200
	s_waitcnt vmcnt(4)
; #define LAS __attribute__((address_space(3)))
; __device__ __forceinline__ unsigned pk2(float lo, float hi) { return pg8::cvt_pk_bf16(lo, hi); }
; __device__ __forceinline__ float bflo(unsigned w) { return __uint_as_float(w << 16); }
; __device__ __forceinline__ float bfhi(unsigned w) { return __uint_as_float(w & 0xffff0000u); }
; __device__ __forceinline__ void ret_unit(LAS unsigned char* lds, int u, const bf16* PROJ, const int* pos, const float* dec_f, const float* dec_b, const bf16* ST,
;                                          const float* gn_w, const float* gn_b, bf16* MIX, int tid, const WsRef& wsr) {
;     ...
;     for (int ii = 0; ii < 2; ++ii) { const int it = tid + 512 * ii, dc = it & 7, j = it >> 3; const unsigned qo = (unsigned)WS_PROJ + (unsigned)(((unsigned)(row0 + j) * INC + h * 128 + dc * 8) * 2u);
;         rq1[ii] = ws_load16(wsr, qo); rq2[ii] = ws_load16(wsr, qo + 128u); rk1[ii] = ws_load16(wsr, qo + 1024u); rk2[ii] = ws_load16(wsr, qo + 1152u); rp[ii] = (float)pos[row0 + j]; }
; #pragma unroll
;     for (int ii = 0; ii < 2; ++ii) { const int it = tid + 512 * ii, dc = it & 7, j = it >> 3;
;         const u32x4 q1 = rq1[ii], q2 = rq2[ii], k1 = rk1[ii], k2 = rk2[ii];
;         const float p = rp[ii];
;         float sn[8], cs[8];
; #pragma unroll
;         for (int e = 0; e < 8; ++e) { const int i = dc * 8 + e; const float inv = fexp2(-(float)i * 0.20762050593046015f); fast_sincos(p * inv, sn[e], cs[e]); }
;         u32x4 oq1, oq2, ok1, ok2;
; #pragma unroll
;         for (int e = 0; e < 4; ++e) { const int e0 = 2 * e, e1 = 2 * e + 1;
;             const float a0 = bflo(q1[e]), a1 = bfhi(q1[e]), b0 = bflo(q2[e]), b1 = bfhi(q2[e]);
;             oq1[e] = pk2(a0 * cs[e0] - b0 * sn[e0], a1 * cs[e1] - b1 * sn[e1]); oq2[e] = pk2(b0 * cs[e0] + a0 * sn[e0], b1 * cs[e1] + a1 * sn[e1]);
;             const float c0 = bflo(k1[e]) * 0.08838834764831845f, c1 = bfhi(k1[e]) * 0.08838834764831845f, d0 = bflo(k2[e]) * 0.08838834764831845f, d1 = bfhi(k2[e]) * 0.08838834764831845f;
;             ok1[e] = pk2(c0 * cs[e0] - d0 * sn[e0], c1 * cs[e1] - d1 * sn[e1]); ok2[e] = pk2(d0 * cs[e0] + c0 * sn[e0], d1 * cs[e1] + c1 * sn[e1]); }
;         *(LAS u32x4*)(Qs + j * LDT + dc * 8) = oq1; *(LAS u32x4*)(Qs + j * LDT + 64 + dc * 8) = oq2;
;         *(LAS u32x4*)(Ks + j * LDT + dc * 8) = ok1; *(LAS u32x4*)(Ks + j * LDT + 64 + dc * 8) = ok2; }
	v_lshlrev_b32_e32 v82, 16, v50
	s_waitcnt vmcnt(3)
	v_lshlrev_b32_e32 v84, 16, v54
	v_and_b32_e32 v85, 0xffff0000, v54
	v_and_b32_e32 v83, 0xffff0000, v50
	s_waitcnt vmcnt(0)
	v_cvt_f32_i32_e32 v49, v0
	v_mul_lo_u32 v0, v66, s9
	v_or_b32_e32 v0, v0, v2
	v_lshl_add_u32 v0, v0, 1, v229
	v_lshl_add_u64 v[66:67], v[66:67], 2, s[12:13]
	buffer_load_dwordx4 v[44:47], v0, s[88:91], 0 offen
	buffer_load_dwordx4 v[40:43], v0, s[88:91], 0 offen offset:128
	buffer_load_dwordx4 v[28:31], v0, s[88:91], 0 offen offset:1024
	s_nop 0
	buffer_load_dwordx4 v[0:3], v0, s[88:91], 0 offen offset:1152
	v_mul_f32_e32 v70, v109, v49
	global_load_dword v66, v[66:67], off
	v_mul_f32_e32 v71, 0.15915494, v70
	v_rndne_f32_e32 v71, v71
	v_fmac_f32_e32 v70, 0xc0c90000, v71
	v_fmac_f32_e32 v70, 0xbafdaa22, v71
	v_mul_f32_e32 v71, 0.15915494, v70
	v_sin_f32_e32 v70, v71
	v_cos_f32_e32 v72, v71
	v_mul_f32_e32 v71, v110, v49
	v_mul_f32_e32 v73, 0.15915494, v71
	v_mul_f32_e32 v74, v111, v49
	v_rndne_f32_e32 v73, v73
	v_mul_f32_e32 v75, 0.15915494, v74
	v_fmac_f32_e32 v71, 0xc0c90000, v73
	v_rndne_f32_e32 v75, v75
	v_fmac_f32_e32 v71, 0xbafdaa22, v73
	v_fmac_f32_e32 v74, 0xc0c90000, v75
	v_mul_f32_e32 v73, 0.15915494, v71
	v_fmac_f32_e32 v74, 0xbafdaa22, v75
	v_sin_f32_e32 v71, v73
	v_mul_f32_e32 v75, 0.15915494, v74
	v_cos_f32_e32 v73, v73
	v_sin_f32_e32 v74, v75
	v_cos_f32_e32 v76, v75
	v_mul_f32_e32 v75, v112, v49
	v_mul_f32_e32 v77, 0.15915494, v75
	v_rndne_f32_e32 v77, v77
	v_mul_f32_e32 v78, v113, v49
	v_fmac_f32_e32 v75, 0xc0c90000, v77
	v_mul_f32_e32 v79, 0.15915494, v78
	v_fmac_f32_e32 v75, 0xbafdaa22, v77
	v_rndne_f32_e32 v79, v79
	v_mul_f32_e32 v77, 0.15915494, v75
	v_fmac_f32_e32 v78, 0xc0c90000, v79
	v_sin_f32_e32 v75, v77
	v_fmac_f32_e32 v78, 0xbafdaa22, v79
	v_cos_f32_e32 v77, v77
	v_mul_f32_e32 v79, 0.15915494, v78
	v_sin_f32_e32 v78, v79
	v_cos_f32_e32 v80, v79
	s_waitcnt vmcnt(0)
	v_cvt_f32_i32_e32 v88, v66
	v_mul_f32_e32 v66, v107, v49
	v_mul_f32_e32 v67, 0.15915494, v66
	v_rndne_f32_e32 v67, v67
	v_fmac_f32_e32 v66, 0xc0c90000, v67
	v_fmac_f32_e32 v66, 0xbafdaa22, v67
	v_mul_f32_e32 v67, 0.15915494, v66
	v_sin_f32_e32 v66, v67
	v_cos_f32_e32 v68, v67
	v_mul_f32_e32 v67, v108, v49
	v_mul_f32_e32 v69, 0.15915494, v67
	v_rndne_f32_e32 v69, v69
	v_fmac_f32_e32 v67, 0xc0c90000, v69
	v_fmac_f32_e32 v67, 0xbafdaa22, v69
	v_mul_f32_e32 v69, 0.15915494, v67
	v_sin_f32_e32 v67, v69
	v_cos_f32_e32 v69, v69
	v_mul_f32_e32 v49, v114, v49
	v_mul_f32_e32 v79, 0.15915494, v49
	v_pk_mul_f32 v[86:87], v[66:67], v[84:85]
	v_rndne_f32_e32 v79, v79
	v_pk_fma_f32 v[86:87], v[68:69], v[82:83], v[86:87] neg_lo:[0,0,1] neg_hi:[0,0,1]
	v_pk_mul_f32 v[82:83], v[66:67], v[82:83]
	v_cvt_pk_bf16_f32 v50, v86, v87
	v_pk_fma_f32 v[82:83], v[68:69], v[84:85], v[82:83]
	v_lshlrev_b32_e32 v84, 16, v62
	v_cvt_pk_bf16_f32 v54, v82, v83
	v_lshlrev_b32_e32 v82, 16, v58
	v_and_b32_e32 v83, 0xffff0000, v58
	v_and_b32_e32 v85, 0xffff0000, v62
	v_pk_mul_f32 v[82:83], v[82:83], s[10:11] op_sel_hi:[1,0]
	v_pk_mul_f32 v[84:85], v[84:85], s[10:11] op_sel_hi:[1,0]
	v_fmac_f32_e32 v49, 0xc0c90000, v79
	v_pk_mul_f32 v[86:87], v[84:85], v[66:67]
	v_pk_mul_f32 v[66:67], v[82:83], v[66:67]
	v_pk_fma_f32 v[86:87], v[82:83], v[68:69], v[86:87] neg_lo:[0,0,1] neg_hi:[0,0,1]
	v_pk_fma_f32 v[66:67], v[84:85], v[68:69], v[66:67]
	v_lshlrev_b32_e32 v68, 16, v55
	v_and_b32_e32 v69, 0xffff0000, v55
	v_cvt_pk_bf16_f32 v62, v66, v67
	v_lshlrev_b32_e32 v66, 16, v51
	v_and_b32_e32 v67, 0xffff0000, v51
	v_pk_mul_f32 v[82:83], v[70:71], v[68:69]
	v_fmac_f32_e32 v49, 0xbafdaa22, v79
	v_pk_fma_f32 v[82:83], v[72:73], v[66:67], v[82:83] neg_lo:[0,0,1] neg_hi:[0,0,1]
	v_pk_mul_f32 v[66:67], v[70:71], v[66:67]
	v_cvt_pk_bf16_f32 v51, v82, v83
	v_pk_fma_f32 v[66:67], v[72:73], v[68:69], v[66:67]
	v_lshlrev_b32_e32 v68, 16, v63
	v_and_b32_e32 v69, 0xffff0000, v63
	v_cvt_pk_bf16_f32 v55, v66, v67
	v_lshlrev_b32_e32 v66, 16, v59
	v_and_b32_e32 v67, 0xffff0000, v59
	v_pk_mul_f32 v[68:69], v[68:69], s[10:11] op_sel_hi:[1,0]
	v_pk_mul_f32 v[66:67], v[66:67], s[10:11] op_sel_hi:[1,0]
	v_pk_mul_f32 v[82:83], v[68:69], v[70:71]
	v_mul_f32_e32 v49, 0.15915494, v49
	v_pk_fma_f32 v[82:83], v[66:67], v[72:73], v[82:83] neg_lo:[0,0,1] neg_hi:[0,0,1]
	v_pk_mul_f32 v[66:67], v[66:67], v[70:71]
	v_sin_f32_e32 v79, v49
	v_pk_fma_f32 v[66:67], v[68:69], v[72:73], v[66:67]
	v_lshlrev_b32_e32 v68, 16, v56
	v_and_b32_e32 v69, 0xffff0000, v56
	v_cvt_pk_bf16_f32 v63, v66, v67
	v_lshlrev_b32_e32 v66, 16, v52
	v_and_b32_e32 v67, 0xffff0000, v52
	v_pk_mul_f32 v[70:71], v[74:75], v[68:69]
	v_cos_f32_e32 v81, v49
	v_pk_fma_f32 v[70:71], v[76:77], v[66:67], v[70:71] neg_lo:[0,0,1] neg_hi:[0,0,1]
	v_pk_mul_f32 v[66:67], v[74:75], v[66:67]
	v_cvt_pk_bf16_f32 v52, v70, v71
	v_pk_fma_f32 v[66:67], v[76:77], v[68:69], v[66:67]
	v_lshlrev_b32_e32 v68, 16, v64
	v_and_b32_e32 v69, 0xffff0000, v64
	v_cvt_pk_bf16_f32 v56, v66, v67
	v_lshlrev_b32_e32 v66, 16, v60
	v_and_b32_e32 v67, 0xffff0000, v60
	v_pk_mul_f32 v[68:69], v[68:69], s[10:11] op_sel_hi:[1,0]
	v_pk_mul_f32 v[66:67], v[66:67], s[10:11] op_sel_hi:[1,0]
	v_pk_mul_f32 v[70:71], v[68:69], v[74:75]
	v_mul_f32_e32 v49, v107, v88
	v_pk_fma_f32 v[70:71], v[66:67], v[76:77], v[70:71] neg_lo:[0,0,1] neg_hi:[0,0,1]
	v_pk_mul_f32 v[66:67], v[66:67], v[74:75]
	v_cvt_pk_bf16_f32 v60, v70, v71
	v_pk_fma_f32 v[66:67], v[68:69], v[76:77], v[66:67]
	v_lshlrev_b32_e32 v68, 16, v57
	v_and_b32_e32 v69, 0xffff0000, v57
	v_cvt_pk_bf16_f32 v64, v66, v67
	v_lshlrev_b32_e32 v66, 16, v53
	v_and_b32_e32 v67, 0xffff0000, v53
	v_pk_mul_f32 v[70:71], v[78:79], v[68:69]
	v_cvt_pk_bf16_f32 v58, v86, v87
; #define LAS __attribute__((address_space(3)))
; __device__ __forceinline__ unsigned pk2(float lo, float hi) { return pg8::cvt_pk_bf16(lo, hi); }
; __device__ __forceinline__ float bflo(unsigned w) { return __uint_as_float(w << 16); }
; __device__ __forceinline__ float bfhi(unsigned w) { return __uint_as_float(w & 0xffff0000u); }
; __device__ __forceinline__ float fexp2(float x) { return __builtin_amdgcn_exp2f(x); }
; __device__ __forceinline__ void ret_unit(LAS unsigned char* lds, int u, const bf16* PROJ, const int* pos, const float* dec_f, const float* dec_b, const bf16* ST,
;                                          const float* gn_w, const float* gn_b, bf16* MIX, int tid, const WsRef& wsr) {
;     ...
;     for (int ii = 0; ii < 2; ++ii) { const int it = tid + 512 * ii, dc = it & 7, j = it >> 3;
;         const u32x4 q1 = rq1[ii], q2 = rq2[ii], k1 = rk1[ii], k2 = rk2[ii];
;         const float p = rp[ii];
;         float sn[8], cs[8];
; #pragma unroll
;         for (int e = 0; e < 8; ++e) { const int i = dc * 8 + e; const float inv = fexp2(-(float)i * 0.20762050593046015f); fast_sincos(p * inv, sn[e], cs[e]); }
;         u32x4 oq1, oq2, ok1, ok2;
; #pragma unroll
;         for (int e = 0; e < 4; ++e) { const int e0 = 2 * e, e1 = 2 * e + 1;
;             const float a0 = bflo(q1[e]), a1 = bfhi(q1[e]), b0 = bflo(q2[e]), b1 = bfhi(q2[e]);
;             oq1[e] = pk2(a0 * cs[e0] - b0 * sn[e0], a1 * cs[e1] - b1 * sn[e1]); oq2[e] = pk2(b0 * cs[e0] + a0 * sn[e0], b1 * cs[e1] + a1 * sn[e1]);
;             const float c0 = bflo(k1[e]) * 0.08838834764831845f, c1 = bfhi(k1[e]) * 0.08838834764831845f, d0 = bflo(k2[e]) * 0.08838834764831845f, d1 = bfhi(k2[e]) * 0.08838834764831845f;
;             ok1[e] = pk2(c0 * cs[e0] - d0 * sn[e0], c1 * cs[e1] - d1 * sn[e1]); ok2[e] = pk2(d0 * cs[e0] + c0 * sn[e0], d1 * cs[e1] + c1 * sn[e1]); }
;         *(LAS u32x4*)(Qs + j * LDT + dc * 8) = oq1; *(LAS u32x4*)(Qs + j * LDT + 64 + dc * 8) = oq2;
;         *(LAS u32x4*)(Ks + j * LDT + dc * 8) = ok1; *(LAS u32x4*)(Ks + j * LDT + 64 + dc * 8) = ok2; }
	v_pk_fma_f32 v[70:71], v[80:81], v[66:67], v[70:71] neg_lo:[0,0,1] neg_hi:[0,0,1]
	v_pk_mul_f32 v[66:67], v[78:79], v[66:67]
	v_cvt_pk_bf16_f32 v53, v70, v71
	v_pk_fma_f32 v[66:67], v[80:81], v[68:69], v[66:67]
	v_lshlrev_b32_e32 v68, 16, v65
	v_and_b32_e32 v69, 0xffff0000, v65
	v_cvt_pk_bf16_f32 v57, v66, v67
	v_lshlrev_b32_e32 v66, 16, v61
	v_and_b32_e32 v67, 0xffff0000, v61
	v_pk_mul_f32 v[68:69], v[68:69], s[10:11] op_sel_hi:[1,0]
	v_pk_mul_f32 v[66:67], v[66:67], s[10:11] op_sel_hi:[1,0]
	v_pk_mul_f32 v[70:71], v[68:69], v[78:79]
	v_cvt_pk_bf16_f32 v59, v82, v83
	v_pk_fma_f32 v[70:71], v[66:67], v[80:81], v[70:71] neg_lo:[0,0,1] neg_hi:[0,0,1]
	v_pk_mul_f32 v[66:67], v[66:67], v[78:79]
	v_cvt_pk_bf16_f32 v61, v70, v71
	v_pk_fma_f32 v[66:67], v[68:69], v[80:81], v[66:67]
	v_lshlrev_b32_e32 v68, 16, v40
	v_cvt_pk_bf16_f32 v65, v66, v67
	ds_write_b128 v115, v[50:53]
	ds_write_b128 v115, v[54:57] offset:128
	ds_write_b128 v115, v[58:61] offset:34816
	ds_write_b128 v115, v[62:65] offset:34944
	v_mul_f32_e32 v50, 0.15915494, v49
	v_rndne_f32_e32 v50, v50
	v_fmac_f32_e32 v49, 0xc0c90000, v50
	v_fmac_f32_e32 v49, 0xbafdaa22, v50
	v_mul_f32_e32 v49, 0.15915494, v49
	v_sin_f32_e32 v50, v49
	v_cos_f32_e32 v52, v49
	v_mul_f32_e32 v49, v108, v88
	v_mul_f32_e32 v51, 0.15915494, v49
	v_rndne_f32_e32 v51, v51
	v_fmac_f32_e32 v49, 0xc0c90000, v51
	v_fmac_f32_e32 v49, 0xbafdaa22, v51
	v_mul_f32_e32 v49, 0.15915494, v49
	v_sin_f32_e32 v51, v49
	v_cos_f32_e32 v53, v49
	v_mul_f32_e32 v49, v109, v88
	v_mul_f32_e32 v54, 0.15915494, v49
	v_rndne_f32_e32 v54, v54
	v_fmac_f32_e32 v49, 0xc0c90000, v54
	v_fmac_f32_e32 v49, 0xbafdaa22, v54
	v_mul_f32_e32 v49, 0.15915494, v49
	v_sin_f32_e32 v54, v49
	v_cos_f32_e32 v56, v49
	v_mul_f32_e32 v49, v110, v88
	v_mul_f32_e32 v55, 0.15915494, v49
	v_rndne_f32_e32 v55, v55
	v_fmac_f32_e32 v49, 0xc0c90000, v55
	v_fmac_f32_e32 v49, 0xbafdaa22, v55
	v_mul_f32_e32 v49, 0.15915494, v49
	v_sin_f32_e32 v55, v49
	v_cos_f32_e32 v57, v49
	v_mul_f32_e32 v49, v111, v88
	v_mul_f32_e32 v58, 0.15915494, v49
	v_rndne_f32_e32 v58, v58
	v_fmac_f32_e32 v49, 0xc0c90000, v58
	v_fmac_f32_e32 v49, 0xbafdaa22, v58
	v_mul_f32_e32 v49, 0.15915494, v49
	v_sin_f32_e32 v58, v49
	v_cos_f32_e32 v60, v49
	v_mul_f32_e32 v49, v112, v88
	v_and_b32_e32 v69, 0xffff0000, v40
	v_mul_f32_e32 v59, 0.15915494, v49
	v_lshlrev_b32_e32 v66, 16, v44
	v_and_b32_e32 v67, 0xffff0000, v44
	v_pk_mul_f32 v[70:71], v[50:51], v[68:69]
	v_rndne_f32_e32 v59, v59
	v_pk_fma_f32 v[70:71], v[52:53], v[66:67], v[70:71] neg_lo:[0,0,1] neg_hi:[0,0,1]
	v_pk_mul_f32 v[66:67], v[50:51], v[66:67]
	v_fmac_f32_e32 v49, 0xc0c90000, v59
	v_pk_fma_f32 v[66:67], v[52:53], v[68:69], v[66:67]
	v_fmac_f32_e32 v49, 0xbafdaa22, v59
	v_cvt_pk_bf16_f32 v44, v66, v67
	v_lshlrev_b32_e32 v66, 16, v28
	v_and_b32_e32 v67, 0xffff0000, v28
	v_lshlrev_b32_e32 v68, 16, v0
	v_and_b32_e32 v69, 0xffff0000, v0
	v_mul_f32_e32 v49, 0.15915494, v49
	v_pk_mul_f32 v[66:67], v[66:67], s[10:11] op_sel_hi:[1,0]
	v_pk_mul_f32 v[68:69], v[68:69], s[10:11] op_sel_hi:[1,0]
	v_sin_f32_e32 v59, v49
	v_cos_f32_e32 v61, v49
	v_mul_f32_e32 v49, v113, v88
	v_cvt_pk_bf16_f32 v40, v70, v71
	v_pk_mul_f32 v[70:71], v[68:69], v[50:51]
	v_pk_mul_f32 v[50:51], v[66:67], v[50:51]
	v_mul_f32_e32 v62, 0.15915494, v49
	v_pk_fma_f32 v[70:71], v[66:67], v[52:53], v[70:71] neg_lo:[0,0,1] neg_hi:[0,0,1]
	v_pk_fma_f32 v[50:51], v[68:69], v[52:53], v[50:51]
	v_lshlrev_b32_e32 v52, 16, v41
	v_and_b32_e32 v53, 0xffff0000, v41
	v_rndne_f32_e32 v62, v62
	v_cvt_pk_bf16_f32 v28, v50, v51
	v_lshlrev_b32_e32 v50, 16, v45
	v_and_b32_e32 v51, 0xffff0000, v45
	v_pk_mul_f32 v[66:67], v[54:55], v[52:53]
	v_fmac_f32_e32 v49, 0xc0c90000, v62
	v_pk_fma_f32 v[66:67], v[56:57], v[50:51], v[66:67] neg_lo:[0,0,1] neg_hi:[0,0,1]
	v_pk_mul_f32 v[50:51], v[54:55], v[50:51]
	v_fmac_f32_e32 v49, 0xbafdaa22, v62
	v_pk_fma_f32 v[50:51], v[56:57], v[52:53], v[50:51]
	v_lshlrev_b32_e32 v52, 16, v1
	v_and_b32_e32 v53, 0xffff0000, v1
	v_mul_f32_e32 v49, 0.15915494, v49
	v_cvt_pk_bf16_f32 v45, v50, v51
	v_lshlrev_b32_e32 v50, 16, v29
	v_and_b32_e32 v51, 0xffff0000, v29
	v_pk_mul_f32 v[52:53], v[52:53], s[10:11] op_sel_hi:[1,0]
	v_sin_f32_e32 v62, v49
	v_cos_f32_e32 v64, v49
	v_mul_f32_e32 v49, v114, v88
	v_cvt_pk_bf16_f32 v41, v66, v67
	v_pk_mul_f32 v[50:51], v[50:51], s[10:11] op_sel_hi:[1,0]
	v_pk_mul_f32 v[66:67], v[52:53], v[54:55]
	v_mul_f32_e32 v63, 0.15915494, v49
	v_pk_fma_f32 v[66:67], v[50:51], v[56:57], v[66:67] neg_lo:[0,0,1] neg_hi:[0,0,1]
	v_pk_mul_f32 v[50:51], v[50:51], v[54:55]
	v_rndne_f32_e32 v63, v63
	v_pk_fma_f32 v[50:51], v[52:53], v[56:57], v[50:51]
	v_lshlrev_b32_e32 v52, 16, v42
	v_and_b32_e32 v53, 0xffff0000, v42
	v_fmac_f32_e32 v49, 0xc0c90000, v63
	v_cvt_pk_bf16_f32 v29, v50, v51
	v_lshlrev_b32_e32 v50, 16, v46
	v_and_b32_e32 v51, 0xffff0000, v46
	v_pk_mul_f32 v[54:55], v[58:59], v[52:53]
	v_fmac_f32_e32 v49, 0xbafdaa22, v63
	v_pk_fma_f32 v[54:55], v[60:61], v[50:51], v[54:55] neg_lo:[0,0,1] neg_hi:[0,0,1]
	v_pk_mul_f32 v[50:51], v[58:59], v[50:51]
	v_mul_f32_e32 v49, 0.15915494, v49
	v_pk_fma_f32 v[50:51], v[60:61], v[52:53], v[50:51]
	v_lshlrev_b32_e32 v52, 16, v2
	v_and_b32_e32 v53, 0xffff0000, v2
	v_sin_f32_e32 v63, v49
	v_cvt_pk_bf16_f32 v46, v50, v51
	v_lshlrev_b32_e32 v50, 16, v30
	v_and_b32_e32 v51, 0xffff0000, v30
	v_pk_mul_f32 v[52:53], v[52:53], s[10:11] op_sel_hi:[1,0]
	v_cos_f32_e32 v65, v49
	v_cvt_pk_bf16_f32 v42, v54, v55
	v_pk_mul_f32 v[50:51], v[50:51], s[10:11] op_sel_hi:[1,0]
	v_pk_mul_f32 v[54:55], v[52:53], v[58:59]
	v_cvt_pk_bf16_f32 v0, v70, v71
	v_pk_fma_f32 v[54:55], v[50:51], v[60:61], v[54:55] neg_lo:[0,0,1] neg_hi:[0,0,1]
; #define LAS __attribute__((address_space(3)))
; __device__ __forceinline__ u32x4 ws_load16(const WsRef& w, unsigned byte_off) { return __builtin_bit_cast(u32x4, __builtin_amdgcn_raw_buffer_load_b128(w.r, byte_off, 0, 0)); }
; __device__ __forceinline__ float fexp2(float x) { return __builtin_amdgcn_exp2f(x); }
; #define MFMA16(a, b, c) __builtin_amdgcn_mfma_f32_16x16x32_bf16((a), (b), (c), 0, 0, 0)
; __device__ __forceinline__ void ret_unit(LAS unsigned char* lds, int u, const bf16* PROJ, const int* pos, const float* dec_f, const float* dec_b, const bf16* ST,
;                                          const float* gn_w, const float* gn_b, bf16* MIX, int tid, const WsRef& wsr) {
;     ...
;         *(LAS u32x4*)(Qs + j * LDT + dc * 8) = oq1; *(LAS u32x4*)(Qs + j * LDT + 64 + dc * 8) = oq2;
;         *(LAS u32x4*)(Ks + j * LDT + dc * 8) = ok1; *(LAS u32x4*)(Ks + j * LDT + 64 + dc * 8) = ok2; }
; #pragma unroll
;     for (int ii = 0; ii < 4; ++ii) { const int it = tid + 512 * ii, ec = it & 15, j = it >> 4; rv[ii] = ws_load16(wsr, (unsigned)WS_PROJ + (unsigned)(((unsigned)(row0 + j) * INC + 1024 + h * 128 + ec * 8) * 2u)); }
; #pragma unroll
;     for (int ii = 0; ii < 4; ++ii) { const int it = tid + 512 * ii, ec = it & 15, j = it >> 4; const u32x4 w = rv[ii];
;         const int jsw = (((j >> 3) ^ (ec & 7)) << 3) | (j & 7);
; #pragma unroll
;         for (int e = 0; e < 4; ++e) { VT[(ec * 8 + 2 * e) * LDT + jsw] = (bf16)(w[e] & 0xffffu); VT[(ec * 8 + 2 * e + 1) * LDT + jsw] = (bf16)(w[e] >> 16); } }
;     __syncthreads();
;     const int q = wave * 16 + fr;
;     bf16x8 qf[4];
; #pragma unroll
;     for (int kk = 0; kk < 4; ++kk) qf[kk] = *(const LAS bf16x8*)(Qs + q * LDT + kk * 32 + fq * 8);
;     f32x4 s[8];
; #pragma unroll
;     for (int n = 0; n < 8; ++n) s[n] = (f32x4){0.f, 0.f, 0.f, 0.f};
; #pragma unroll
;     for (int kk = 0; kk < 4; ++kk)
; #pragma unroll
;         for (int n = 0; n < 8; ++n) { const bf16x8 kf = *(const LAS bf16x8*)(Ks + (n * 16 + fr) * LDT + kk * 32 + fq * 8); s[n] = MFMA16(kf, qf[kk], s[n]); }
;     bf16x8 pf[4];
; #pragma unroll
;     for (int n = 0; n < 8; ++n) {
; #pragma unroll
;         for (int r = 0; r < 4; ++r) { const int key = n * 16 + 4 * fq + r; const int df = q - key; const float f = df >= 0 ? fexp2(lgf2 * (float)df) : fexp2(lgb2 * (float)(-df)); s[n][r] *= f; } }
	v_pk_mul_f32 v[50:51], v[50:51], v[58:59]
	v_cvt_pk_bf16_f32 v2, v54, v55
	v_pk_fma_f32 v[50:51], v[52:53], v[60:61], v[50:51]
	v_lshlrev_b32_e32 v52, 16, v43
	v_and_b32_e32 v53, 0xffff0000, v43
	v_cvt_pk_bf16_f32 v30, v50, v51
	v_lshlrev_b32_e32 v50, 16, v47
	v_and_b32_e32 v51, 0xffff0000, v47
	v_pk_mul_f32 v[54:55], v[62:63], v[52:53]
	v_cvt_pk_bf16_f32 v1, v66, v67
	v_pk_fma_f32 v[54:55], v[64:65], v[50:51], v[54:55] neg_lo:[0,0,1] neg_hi:[0,0,1]
	v_pk_mul_f32 v[50:51], v[62:63], v[50:51]
	v_cvt_pk_bf16_f32 v43, v54, v55
	v_pk_fma_f32 v[50:51], v[64:65], v[52:53], v[50:51]
	v_lshlrev_b32_e32 v52, 16, v3
	v_and_b32_e32 v53, 0xffff0000, v3
	v_cvt_pk_bf16_f32 v47, v50, v51
	v_lshlrev_b32_e32 v50, 16, v31
	v_and_b32_e32 v51, 0xffff0000, v31
	v_pk_mul_f32 v[52:53], v[52:53], s[10:11] op_sel_hi:[1,0]
	v_pk_mul_f32 v[50:51], v[50:51], s[10:11] op_sel_hi:[1,0]
	v_pk_mul_f32 v[54:55], v[52:53], v[62:63]
	v_add_u32_e32 v49, v124, v125
	v_pk_fma_f32 v[54:55], v[50:51], v[64:65], v[54:55] neg_lo:[0,0,1] neg_hi:[0,0,1]
	v_pk_mul_f32 v[50:51], v[50:51], v[62:63]
	v_cvt_pk_bf16_f32 v3, v54, v55
	v_pk_fma_f32 v[50:51], v[52:53], v[64:65], v[50:51]
	v_cndmask_b32_e64 v86, v105, v230, s[66:67]
	v_cvt_pk_bf16_f32 v31, v50, v51
	ds_write_b128 v116, v[40:43]
	ds_write_b128 v116, v[44:47] offset:128
	ds_write_b128 v116, v[0:3] offset:34816
	ds_write_b128 v116, v[28:31] offset:34944
	v_or_b32_e32 v44, s0, v222
	v_or_b32_e32 v0, s4, v99
	v_mad_u64_u32 v[0:1], s[68:69], v0, s9, v[44:45]
	v_lshl_add_u32 v0, v0, 1, v229
	buffer_load_dwordx4 v[0:3], v0, s[88:91], 0 offen
	v_or_b32_e32 v28, s4, v117
	v_mad_u64_u32 v[28:29], s[68:69], v28, s9, v[44:45]
	v_lshl_add_u32 v28, v28, 1, v229
	buffer_load_dwordx4 v[28:31], v28, s[88:91], 0 offen
	v_or_b32_e32 v40, s4, v118
	v_mad_u64_u32 v[40:41], s[68:69], v40, s9, v[44:45]
	v_lshl_add_u32 v40, v40, 1, v229
	buffer_load_dwordx4 v[40:43], v40, s[88:91], 0 offen
	v_add_u32_e32 v45, s4, v119
	v_mad_u64_u32 v[44:45], s[68:69], v45, s9, v[44:45]
	v_lshl_add_u32 v44, v44, 1, v229
	buffer_load_dwordx4 v[44:47], v44, s[88:91], 0 offen
	s_waitcnt vmcnt(3)
	ds_write_b16 v120, v0
	ds_write_b16_d16_hi v120, v0 offset:272
	ds_write_b16 v120, v1 offset:544
	ds_write_b16_d16_hi v120, v1 offset:816
	ds_write_b16 v120, v2 offset:1088
	ds_write_b16_d16_hi v120, v2 offset:1360
	ds_write_b16 v120, v3 offset:1632
	ds_write_b16_d16_hi v120, v3 offset:1904
	s_waitcnt vmcnt(2)
	ds_write_b16 v121, v28
	ds_write_b16_d16_hi v121, v28 offset:272
	ds_write_b16 v121, v29 offset:544
	ds_write_b16_d16_hi v121, v29 offset:816
	ds_write_b16 v121, v30 offset:1088
	ds_write_b16_d16_hi v121, v30 offset:1360
	ds_write_b16 v121, v31 offset:1632
	ds_write_b16_d16_hi v121, v31 offset:1904
	s_waitcnt vmcnt(1)
	ds_write_b16 v122, v40
	ds_write_b16_d16_hi v122, v40 offset:272
	ds_write_b16 v122, v41 offset:544
	ds_write_b16_d16_hi v122, v41 offset:816
	ds_write_b16 v122, v42 offset:1088
	ds_write_b16_d16_hi v122, v42 offset:1360
	ds_write_b16 v122, v43 offset:1632
	ds_write_b16_d16_hi v122, v43 offset:1904
	s_waitcnt vmcnt(0)
	ds_write_b16 v123, v44
	ds_write_b16_d16_hi v123, v44 offset:272
	ds_write_b16 v123, v45 offset:544
	ds_write_b16_d16_hi v123, v45 offset:816
	ds_write_b16 v123, v46 offset:1088
	ds_write_b16_d16_hi v123, v46 offset:1360
	ds_write_b16 v123, v47 offset:1632
	ds_write_b16_d16_hi v123, v47 offset:1904
	s_waitcnt lgkmcnt(0)
	s_barrier
	ds_read_b128 v[44:47], v225
	ds_read_b128 v[40:43], v225 offset:64
	ds_read_b128 v[28:31], v225 offset:128
	ds_read_b128 v[0:3], v225 offset:192
	ds_read_b128 v[50:53], v226 offset:34816
	ds_read_b128 v[54:57], v226 offset:39168
	ds_read_b128 v[82:85], v226 offset:34880
	s_waitcnt lgkmcnt(2)
	v_mfma_f32_16x16x32_bf16 v[50:53], v[50:53], v[44:47], 0
	ds_read_b128 v[58:61], v226 offset:43520
	ds_read_b128 v[62:65], v226 offset:47872
	ds_read_b128 v[66:69], v226 offset:52224
	s_waitcnt lgkmcnt(3)
	v_mfma_f32_16x16x32_bf16 v[50:53], v[82:85], v[40:43], v[50:53]
	ds_read_b128 v[82:85], v226 offset:39232
	ds_read_b128 v[70:73], v49 offset:34816
	ds_read_b128 v[74:77], v49 offset:39168
	v_mfma_f32_16x16x32_bf16 v[54:57], v[54:57], v[44:47], 0
	ds_read_b128 v[78:81], v49 offset:43520
	v_cndmask_b32_e64 v87, v105, v230, s[26:27]
	v_cndmask_b32_e64 v88, v105, v230, s[28:29]
	s_waitcnt lgkmcnt(3)
	v_mfma_f32_16x16x32_bf16 v[54:57], v[82:85], v[40:43], v[54:57]
	ds_read_b128 v[82:85], v226 offset:43584
	v_mul_f32_e32 v86, v86, v134
	v_mul_f32_e32 v87, v87, v135
	v_mfma_f32_16x16x32_bf16 v[58:61], v[58:61], v[44:47], 0
	v_mul_f32_e32 v88, v88, v136
	v_exp_f32_e32 v86, v86
	v_exp_f32_e32 v87, v87
	s_waitcnt lgkmcnt(0)
	v_mfma_f32_16x16x32_bf16 v[58:61], v[82:85], v[40:43], v[58:61]
	ds_read_b128 v[82:85], v226 offset:47936
	v_exp_f32_e32 v88, v88
	v_readlane_b32 s68, v255, 4
	v_mfma_f32_16x16x32_bf16 v[62:65], v[62:65], v[44:47], 0
	v_readlane_b32 s69, v255, 5
	s_waitcnt lgkmcnt(0)
	v_mfma_f32_16x16x32_bf16 v[62:65], v[82:85], v[40:43], v[62:65]
	ds_read_b128 v[82:85], v226 offset:52288
	v_cndmask_b32_e64 v239, v105, v230, s[68:69]
	v_readlane_b32 s68, v255, 50
	v_mfma_f32_16x16x32_bf16 v[66:69], v[66:69], v[44:47], 0
	v_readlane_b32 s69, v255, 51
	v_mul_f32_e32 v239, v239, v155
	v_exp_f32_e32 v239, v239
	s_waitcnt lgkmcnt(0)
	v_mfma_f32_16x16x32_bf16 v[66:69], v[82:85], v[40:43], v[66:69]
	ds_read_b128 v[82:85], v49 offset:34880
	v_cndmask_b32_e64 v240, v105, v230, s[68:69]
	v_readlane_b32 s68, v255, 52
	v_mfma_f32_16x16x32_bf16 v[70:73], v[70:73], v[44:47], 0
	v_readlane_b32 s69, v255, 53
	v_mul_f32_e32 v240, v240, v156
	v_exp_f32_e32 v240, v240
	s_waitcnt lgkmcnt(0)
; #define LAS __attribute__((address_space(3)))
; __device__ __forceinline__ unsigned pk2(float lo, float hi) { return pg8::cvt_pk_bf16(lo, hi); }
; __device__ __forceinline__ float fexp2(float x) { return __builtin_amdgcn_exp2f(x); }
; #define MFMA16(a, b, c) __builtin_amdgcn_mfma_f32_16x16x32_bf16((a), (b), (c), 0, 0, 0)
; __device__ __forceinline__ void ret_unit(LAS unsigned char* lds, int u, const bf16* PROJ, const int* pos, const float* dec_f, const float* dec_b, const bf16* ST,
;                                          const float* gn_w, const float* gn_b, bf16* MIX, int tid, const WsRef& wsr) {
;     ...
;     for (int kk = 0; kk < 4; ++kk)
; #pragma unroll
;         for (int n = 0; n < 8; ++n) { const bf16x8 kf = *(const LAS bf16x8*)(Ks + (n * 16 + fr) * LDT + kk * 32 + fq * 8); s[n] = MFMA16(kf, qf[kk], s[n]); }
;     bf16x8 pf[4];
; #pragma unroll
;     for (int n = 0; n < 8; ++n) {
; #pragma unroll
;         for (int r = 0; r < 4; ++r) { const int key = n * 16 + 4 * fq + r; const int df = q - key; const float f = df >= 0 ? fexp2(lgf2 * (float)df) : fexp2(lgb2 * (float)(-df)); s[n][r] *= f; } }
; #pragma unroll
;     for (int kk = 0; kk < 4; ++kk) { u32x4 w; w.x = pk2(s[2 * kk][0], s[2 * kk][1]); w.y = pk2(s[2 * kk][2], s[2 * kk][3]); w.z = pk2(s[2 * kk + 1][0], s[2 * kk + 1][1]); w.w = pk2(s[2 * kk + 1][2], s[2 * kk + 1][3]);
;         pf[kk] = __builtin_bit_cast(bf16x8, w); }
;     f32x4 o[8];
; #pragma unroll
;     for (int n = 0; n < 8; ++n) o[n] = (f32x4){0.f, 0.f, 0.f, 0.f};
; #pragma unroll
;     for (int kk = 0; kk < 4; ++kk)
; #pragma unroll
;         for (int n = 0; n < 8; ++n) { const int sw = (2 * n + (fr >> 3)) & 7, jc = kk * 4 + (fq >> 1); const LAS bf16* vr = VT + (n * 16 + fr) * LDT + 4 * (fq & 1);
;             const u32x2 lo = *(const LAS u32x2*)(vr + ((jc ^ sw) << 3)), hi = *(const LAS u32x2*)(vr + (((jc + 2) ^ sw) << 3)); u32x4 w; w.x = lo.x; w.y = lo.y; w.z = hi.x; w.w = hi.y;
;             o[n] = MFMA16(__builtin_bit_cast(bf16x8, w), pf[kk], o[n]); }
	v_mfma_f32_16x16x32_bf16 v[70:73], v[82:85], v[40:43], v[70:73]
	ds_read_b128 v[82:85], v49 offset:39232
	v_cndmask_b32_e64 v241, v105, v230, s[68:69]
	v_readlane_b32 s68, v255, 54
	v_mfma_f32_16x16x32_bf16 v[74:77], v[74:77], v[44:47], 0
	v_readlane_b32 s69, v255, 55
	v_mul_f32_e32 v241, v241, v157
	v_exp_f32_e32 v241, v241
	s_waitcnt lgkmcnt(0)
	v_mfma_f32_16x16x32_bf16 v[74:77], v[82:85], v[40:43], v[74:77]
	ds_read_b128 v[82:85], v49 offset:43584
	v_cndmask_b32_e64 v242, v105, v230, s[68:69]
	v_readlane_b32 s68, v255, 56
	v_mfma_f32_16x16x32_bf16 v[78:81], v[78:81], v[44:47], 0
	v_readlane_b32 s69, v255, 57
	v_mul_f32_e32 v242, v242, v158
	v_exp_f32_e32 v242, v242
	s_waitcnt lgkmcnt(0)
	v_mfma_f32_16x16x32_bf16 v[78:81], v[82:85], v[40:43], v[78:81]
	ds_read_b128 v[82:85], v226 offset:34944
	v_cndmask_b32_e64 v243, v105, v230, s[68:69]
	v_mul_f32_e32 v243, v243, v159
	s_waitcnt lgkmcnt(0)
	v_mfma_f32_16x16x32_bf16 v[50:53], v[82:85], v[28:31], v[50:53]
	ds_read_b128 v[82:85], v226 offset:39296
	v_exp_f32_e32 v243, v243
	s_waitcnt lgkmcnt(0)
	v_mfma_f32_16x16x32_bf16 v[54:57], v[82:85], v[28:31], v[54:57]
	ds_read_b128 v[82:85], v226 offset:43648
	s_waitcnt lgkmcnt(0)
	v_mfma_f32_16x16x32_bf16 v[58:61], v[82:85], v[28:31], v[58:61]
	ds_read_b128 v[82:85], v226 offset:48000
	s_waitcnt lgkmcnt(0)
	v_mfma_f32_16x16x32_bf16 v[62:65], v[82:85], v[28:31], v[62:65]
	ds_read_b128 v[82:85], v226 offset:52352
	s_waitcnt lgkmcnt(0)
	v_mfma_f32_16x16x32_bf16 v[66:69], v[82:85], v[28:31], v[66:69]
	ds_read_b128 v[82:85], v49 offset:34944
	s_waitcnt lgkmcnt(0)
	v_mfma_f32_16x16x32_bf16 v[70:73], v[82:85], v[28:31], v[70:73]
	ds_read_b128 v[82:85], v49 offset:39296
	s_waitcnt lgkmcnt(0)
	v_mfma_f32_16x16x32_bf16 v[74:77], v[82:85], v[28:31], v[74:77]
	ds_read_b128 v[82:85], v49 offset:43648
	s_waitcnt lgkmcnt(0)
	v_mfma_f32_16x16x32_bf16 v[78:81], v[82:85], v[28:31], v[78:81]
	ds_read_b128 v[82:85], v226 offset:35008
	s_waitcnt lgkmcnt(0)
	v_mfma_f32_16x16x32_bf16 v[50:53], v[82:85], v[0:3], v[50:53]
	ds_read_b128 v[82:85], v226 offset:39360
	s_waitcnt lgkmcnt(0)
	v_mfma_f32_16x16x32_bf16 v[54:57], v[82:85], v[0:3], v[54:57]
	ds_read_b128 v[82:85], v226 offset:43712
	s_nop 6
	v_pk_mul_f32 v[56:57], v[86:87], v[56:57]
	s_waitcnt lgkmcnt(0)
	v_mfma_f32_16x16x32_bf16 v[58:61], v[82:85], v[0:3], v[58:61]
	ds_read_b128 v[82:85], v226 offset:48064
	s_nop 6
	v_pk_mul_f32 v[58:59], v[88:89], v[58:59]
	s_waitcnt lgkmcnt(0)
	v_mfma_f32_16x16x32_bf16 v[62:65], v[82:85], v[0:3], v[62:65]
	ds_read_b128 v[82:85], v226 offset:52416
	v_pk_mul_f32 v[88:89], v[90:91], v[60:61]
	s_nop 5
	v_pk_mul_f32 v[64:65], v[94:95], v[64:65]
	s_waitcnt lgkmcnt(0)
	v_mfma_f32_16x16x32_bf16 v[66:69], v[82:85], v[0:3], v[66:69]
	ds_read_b128 v[82:85], v49 offset:35008
	v_pk_mul_f32 v[92:93], v[92:93], v[62:63]
	v_cvt_pk_bf16_f32 v63, v56, v57
	v_cvt_pk_bf16_f32 v56, v58, v59
	v_cvt_pk_bf16_f32 v59, v64, v65
	v_add_u32_e32 v64, v160, v161
	ds_read_b64 v[64:65], v64
	s_waitcnt lgkmcnt(1)
	v_mfma_f32_16x16x32_bf16 v[70:73], v[82:85], v[0:3], v[70:73]
	ds_read_b128 v[82:85], v49 offset:39360
	v_cvt_pk_bf16_f32 v58, v92, v93
	v_add_u32_e32 v92, v175, v170
	ds_read_b64 v[92:93], v92
	s_waitcnt lgkmcnt(1)
	v_mfma_f32_16x16x32_bf16 v[74:77], v[82:85], v[0:3], v[74:77]
	ds_read_b128 v[82:85], v49 offset:43712
	v_add_u32_e32 v94, v175, v171
	ds_read_b64 v[94:95], v94
	s_waitcnt lgkmcnt(1)
	v_mfma_f32_16x16x32_bf16 v[78:81], v[82:85], v[0:3], v[78:81]
	v_cndmask_b32_e64 v49, v105, v230, s[44:45]
	v_cndmask_b32_e64 v82, v105, v230, s[46:47]
	v_cndmask_b32_e64 v83, v105, v230, s[48:49]
	v_mul_f32_e32 v49, v49, v129
	v_mul_f32_e32 v82, v82, v231
	v_mul_f32_e32 v83, v83, v252
	v_exp_f32_e32 v49, v49
	v_exp_f32_e32 v82, v82
	v_exp_f32_e32 v83, v83
	v_pk_mul_f32 v[66:67], v[130:131], v[66:67]
	v_pk_mul_f32 v[48:49], v[48:49], v[50:51]
	v_cndmask_b32_e64 v84, v105, v230, s[50:51]
	v_pk_mul_f32 v[50:51], v[82:83], v[52:53]
	v_cvt_pk_bf16_f32 v52, v66, v67
	v_add_u32_e32 v66, v160, v162
	ds_read_b64 v[66:67], v66
	v_cndmask_b32_e64 v85, v105, v230, s[52:53]
	v_mul_f32_e32 v84, v84, v253
	v_mul_f32_e32 v85, v85, v254
	v_exp_f32_e32 v84, v84
	v_exp_f32_e32 v85, v85
	v_cvt_pk_bf16_f32 v60, v48, v49
	v_cvt_pk_bf16_f32 v61, v50, v51
	v_pk_mul_f32 v[80:81], v[242:243], v[80:81]
	v_pk_mul_f32 v[54:55], v[84:85], v[54:55]
	v_cvt_pk_bf16_f32 v51, v80, v81
	v_cvt_pk_bf16_f32 v62, v54, v55
	v_cvt_pk_bf16_f32 v57, v88, v89
	v_pk_mul_f32 v[78:79], v[240:241], v[78:79]
	s_waitcnt lgkmcnt(0)
	v_mfma_f32_16x16x32_bf16 v[84:87], v[64:67], v[60:63], 0
	v_add_u32_e32 v64, v163, v164
	v_add_u32_e32 v66, v163, v165
	ds_read_b64 v[64:65], v64
	ds_read_b64 v[66:67], v66
	s_waitcnt lgkmcnt(0)
	v_mfma_f32_16x16x32_bf16 v[80:83], v[64:67], v[60:63], 0
	v_add_u32_e32 v64, v166, v167
	v_add_u32_e32 v66, v166, v168
	ds_read_b64 v[64:65], v64
	ds_read_b64 v[66:67], v66
	s_waitcnt lgkmcnt(0)
	v_mfma_f32_16x16x32_bf16 v[88:91], v[64:67], v[60:63], 0
	v_add_u32_e32 v64, v169, v170
	v_add_u32_e32 v66, v169, v171
	ds_read_b64 v[64:65], v64
	ds_read_b64 v[66:67], v66
	v_pk_mul_f32 v[76:77], v[238:239], v[76:77]
	v_cvt_pk_bf16_f32 v50, v78, v79
	v_cvt_pk_bf16_f32 v49, v76, v77
	s_waitcnt lgkmcnt(0)
	v_mfma_f32_16x16x32_bf16 v[76:79], v[64:67], v[60:63], 0
	v_add_u32_e32 v64, v172, v161
	v_add_u32_e32 v66, v172, v162
	ds_read_b64 v[64:65], v64
	ds_read_b64 v[66:67], v66
	v_pk_mul_f32 v[74:75], v[236:237], v[74:75]
	v_pk_mul_f32 v[72:73], v[234:235], v[72:73]
	v_cvt_pk_bf16_f32 v48, v74, v75
	v_cvt_pk_bf16_f32 v55, v72, v73
	s_waitcnt lgkmcnt(0)
; #define LAS __attribute__((address_space(3)))
; #define MFMA16(a, b, c) __builtin_amdgcn_mfma_f32_16x16x32_bf16((a), (b), (c), 0, 0, 0)
; __device__ __forceinline__ void ret_unit(LAS unsigned char* lds, int u, const bf16* PROJ, const int* pos, const float* dec_f, const float* dec_b, const bf16* ST,
;                                          const float* gn_w, const float* gn_b, bf16* MIX, int tid, const WsRef& wsr) {
;     ...
; #pragma unroll
;     for (int kk = 0; kk < 4; ++kk)
; #pragma unroll
;         for (int n = 0; n < 8; ++n) { const int sw = (2 * n + (fr >> 3)) & 7, jc = kk * 4 + (fq >> 1); const LAS bf16* vr = VT + (n * 16 + fr) * LDT + 4 * (fq & 1);
;             const u32x2 lo = *(const LAS u32x2*)(vr + ((jc ^ sw) << 3)), hi = *(const LAS u32x2*)(vr + (((jc + 2) ^ sw) << 3)); u32x4 w; w.x = lo.x; w.y = lo.y; w.z = hi.x; w.w = hi.y;
;             o[n] = MFMA16(__builtin_bit_cast(bf16x8, w), pf[kk], o[n]); }
;     __syncthreads();
; #pragma unroll
;     for (int i = 0; i < 4; ++i) { const int id = tid + 512 * i, e = id >> 4, dch = id & 15;
;         *(LAS u32x4*)(Ks + e * LDT + dch * 8) = sf[i]; *(LAS u32x4*)(VT + e * LDT + dch * 8) = sb[i]; }
;     __syncthreads();
	v_mfma_f32_16x16x32_bf16 v[72:75], v[64:67], v[60:63], 0
	v_add_u32_e32 v64, v173, v164
	v_add_u32_e32 v66, v173, v165
	ds_read_b64 v[64:65], v64
	ds_read_b64 v[66:67], v66
	v_pk_mul_f32 v[70:71], v[232:233], v[70:71]
	v_pk_mul_f32 v[68:69], v[132:133], v[68:69]
	v_cvt_pk_bf16_f32 v54, v70, v71
	v_cvt_pk_bf16_f32 v53, v68, v69
	s_waitcnt lgkmcnt(0)
	v_mfma_f32_16x16x32_bf16 v[68:71], v[64:67], v[60:63], 0
	v_add_u32_e32 v64, v174, v167
	v_add_u32_e32 v66, v174, v168
	ds_read_b64 v[64:65], v64
	ds_read_b64 v[66:67], v66
	s_waitcnt lgkmcnt(0)
	v_mfma_f32_16x16x32_bf16 v[64:67], v[64:67], v[60:63], 0
	v_mfma_f32_16x16x32_bf16 v[60:63], v[92:95], v[60:63], 0
	v_add_u32_e32 v92, v160, v176
	v_add_u32_e32 v94, v160, v177
	ds_read_b64 v[92:93], v92
	ds_read_b64 v[94:95], v94
	s_waitcnt lgkmcnt(0)
	v_mfma_f32_16x16x32_bf16 v[84:87], v[92:95], v[56:59], v[84:87]
	v_add_u32_e32 v92, v163, v178
	v_add_u32_e32 v94, v163, v179
	ds_read_b64 v[92:93], v92
	ds_read_b64 v[94:95], v94
	s_waitcnt lgkmcnt(0)
	v_mfma_f32_16x16x32_bf16 v[80:83], v[92:95], v[56:59], v[80:83]
	v_add_u32_e32 v92, v166, v180
	v_add_u32_e32 v94, v166, v181
	ds_read_b64 v[92:93], v92
	ds_read_b64 v[94:95], v94
	s_waitcnt lgkmcnt(0)
	v_mfma_f32_16x16x32_bf16 v[88:91], v[92:95], v[56:59], v[88:91]
	v_add_u32_e32 v92, v169, v182
	v_add_u32_e32 v94, v169, v183
	ds_read_b64 v[92:93], v92
	ds_read_b64 v[94:95], v94
	s_waitcnt lgkmcnt(0)
	v_mfma_f32_16x16x32_bf16 v[92:95], v[92:95], v[56:59], v[76:79]
	s_nop 2
	v_add_u32_e32 v76, v172, v176
	v_add_u32_e32 v78, v172, v177
	ds_read_b64 v[76:77], v76
	ds_read_b64 v[78:79], v78
	s_waitcnt lgkmcnt(0)
	v_mfma_f32_16x16x32_bf16 v[72:75], v[76:79], v[56:59], v[72:75]
	v_add_u32_e32 v76, v173, v178
	v_add_u32_e32 v78, v173, v179
	ds_read_b64 v[76:77], v76
	ds_read_b64 v[78:79], v78
	s_waitcnt lgkmcnt(0)
	v_mfma_f32_16x16x32_bf16 v[68:71], v[76:79], v[56:59], v[68:71]
	v_add_u32_e32 v76, v174, v180
	v_add_u32_e32 v78, v174, v181
	ds_read_b64 v[76:77], v76
	ds_read_b64 v[78:79], v78
	s_waitcnt lgkmcnt(0)
	v_mfma_f32_16x16x32_bf16 v[64:67], v[76:79], v[56:59], v[64:67]
	v_add_u32_e32 v76, v175, v182
	v_add_u32_e32 v78, v175, v183
	ds_read_b64 v[76:77], v76
	ds_read_b64 v[78:79], v78
	s_waitcnt lgkmcnt(0)
	v_mfma_f32_16x16x32_bf16 v[56:59], v[76:79], v[56:59], v[60:63]
	v_add_u32_e32 v76, v163, v186
	v_add_u32_e32 v78, v163, v187
	ds_read_b64 v[76:77], v76
	ds_read_b64 v[78:79], v78
	s_waitcnt lgkmcnt(0)
	v_mfma_f32_16x16x32_bf16 v[76:79], v[76:79], v[52:55], v[80:83]
	s_nop 2
	v_add_u32_e32 v80, v166, v188
	v_add_u32_e32 v82, v166, v189
	ds_read_b64 v[80:81], v80
	ds_read_b64 v[82:83], v82
	s_waitcnt lgkmcnt(0)
	v_mfma_f32_16x16x32_bf16 v[80:83], v[80:83], v[52:55], v[88:91]
	s_nop 2
	v_add_u32_e32 v88, v172, v184
	v_add_u32_e32 v90, v172, v185
	ds_read_b64 v[88:89], v88
	ds_read_b64 v[90:91], v90
	s_waitcnt lgkmcnt(0)
	v_mfma_f32_16x16x32_bf16 v[72:75], v[88:91], v[52:55], v[72:75]
	v_add_u32_e32 v88, v173, v186
	v_add_u32_e32 v90, v173, v187
	v_add_u32_e32 v60, v160, v184
	v_add_u32_e32 v62, v160, v185
	ds_read_b64 v[88:89], v88
	ds_read_b64 v[90:91], v90
	ds_read_b64 v[60:61], v60
	ds_read_b64 v[62:63], v62
	s_waitcnt lgkmcnt(2)
	v_mfma_f32_16x16x32_bf16 v[88:91], v[88:91], v[52:55], v[68:71]
	s_nop 2
	v_add_u32_e32 v68, v174, v188
	v_add_u32_e32 v70, v174, v189
	ds_read_b64 v[68:69], v68
	ds_read_b64 v[70:71], v70
	s_waitcnt lgkmcnt(2)
	v_mfma_f32_16x16x32_bf16 v[60:63], v[60:63], v[52:55], v[84:87]
	s_nop 2
	v_add_u32_e32 v84, v169, v190
	v_add_u32_e32 v86, v169, v191
	ds_read_b64 v[84:85], v84
	ds_read_b64 v[86:87], v86
	s_waitcnt lgkmcnt(0)
	v_mfma_f32_16x16x32_bf16 v[84:87], v[84:87], v[52:55], v[92:95]
	v_mfma_f32_16x16x32_bf16 v[92:95], v[68:71], v[52:55], v[64:67]
	v_add_u32_e32 v68, v172, v192
	v_add_u32_e32 v70, v172, v193
	ds_read_b64 v[68:69], v68
	ds_read_b64 v[70:71], v70
	v_add_u32_e32 v64, v175, v190
	v_add_u32_e32 v66, v175, v191
	ds_read_b64 v[64:65], v64
	ds_read_b64 v[66:67], v66
	s_waitcnt lgkmcnt(0)
	v_mfma_f32_16x16x32_bf16 v[232:235], v[64:67], v[52:55], v[56:59]
	v_add_u32_e32 v52, v160, v192
	v_add_u32_e32 v54, v160, v193
	ds_read_b64 v[52:53], v52
	ds_read_b64 v[54:55], v54
	v_add_u32_e32 v56, v163, v194
	v_add_u32_e32 v58, v163, v195
	ds_read_b64 v[56:57], v56
	ds_read_b64 v[58:59], v58
	s_waitcnt lgkmcnt(2)
	v_mfma_f32_16x16x32_bf16 v[52:55], v[52:55], v[48:51], v[60:63]
	s_nop 2
	v_add_u32_e32 v60, v166, v196
	v_add_u32_e32 v62, v166, v197
	ds_read_b64 v[60:61], v60
	ds_read_b64 v[62:63], v62
	v_add_u32_e32 v64, v169, v198
	v_add_u32_e32 v66, v169, v199
	s_waitcnt lgkmcnt(2)
	v_mfma_f32_16x16x32_bf16 v[56:59], v[56:59], v[48:51], v[76:79]
	ds_read_b64 v[64:65], v64
	ds_read_b64 v[66:67], v66
	s_waitcnt lgkmcnt(2)
	v_mfma_f32_16x16x32_bf16 v[60:63], v[60:63], v[48:51], v[80:83]
	v_add_u32_e32 v76, v174, v196
	v_add_u32_e32 v78, v174, v197
	s_nop 0
	v_add_u32_e32 v80, v175, v198
	v_mfma_f32_16x16x32_bf16 v[68:71], v[68:71], v[48:51], v[72:75]
	v_add_u32_e32 v82, v175, v199
	ds_read_b64 v[76:77], v76
	ds_read_b64 v[78:79], v78
	v_add_u32_e32 v72, v173, v194
	v_add_u32_e32 v74, v173, v195
	ds_read_b64 v[72:73], v72
	ds_read_b64 v[74:75], v74
	ds_read_b64 v[80:81], v80
	ds_read_b64 v[82:83], v82
	s_waitcnt lgkmcnt(0)
	s_barrier
	ds_write_b128 v200, v[4:7] offset:34816
	ds_write_b128 v201, v[12:15]
	ds_write_b128 v202, v[8:11] offset:34816
	ds_write_b128 v203, v[16:19]
	ds_write_b128 v205, v[24:27] offset:34816
	ds_write_b128 v206, v[20:23]
	ds_write_b128 v207, v[32:35] offset:34816
	ds_write_b128 v208, v[36:39]
	s_waitcnt lgkmcnt(0)
	s_barrier
; #define LAS __attribute__((address_space(3)))
; #define MFMA16(a, b, c) __builtin_amdgcn_mfma_f32_16x16x32_bf16((a), (b), (c), 0, 0, 0)
; __device__ __forceinline__ void ret_unit(LAS unsigned char* lds, int u, const bf16* PROJ, const int* pos, const float* dec_f, const float* dec_b, const bf16* ST,
;                                          const float* gn_w, const float* gn_b, bf16* MIX, int tid, const WsRef& wsr) {
;     ...
;     {
;         f32x4 tf[8], tb[8];
; #pragma unroll
;         for (int n = 0; n < 8; ++n) { tf[n] = (f32x4){0.f, 0.f, 0.f, 0.f}; tb[n] = (f32x4){0.f, 0.f, 0.f, 0.f}; }
; #pragma unroll
;         for (int kk = 0; kk < 4; ++kk)
; #pragma unroll
;             for (int n = 0; n < 8; ++n) { const bf16x8 yf = *(const LAS bf16x8*)(Ks + (n * 16 + fr) * LDT + kk * 32 + fq * 8); const bf16x8 yb = *(const LAS bf16x8*)(VT + (n * 16 + fr) * LDT + kk * 32 + fq * 8);
;                 tf[n] = MFMA16(yf, qf[kk], tf[n]); tb[n] = MFMA16(yb, qf[kk], tb[n]); }
	ds_read_b128 v[4:7], v209 offset:34816
	ds_read_b128 v[8:11], v210
	s_waitcnt lgkmcnt(1)
	v_mfma_f32_16x16x32_bf16 v[12:15], v[4:7], v[44:47], 0
	s_waitcnt lgkmcnt(0)
	v_mfma_f32_16x16x32_bf16 v[16:19], v[8:11], v[44:47], 0
	ds_read_b128 v[4:7], v209 offset:39168
	ds_read_b128 v[8:11], v211
	s_waitcnt lgkmcnt(1)
	v_mfma_f32_16x16x32_bf16 v[32:35], v[4:7], v[44:47], 0
	s_waitcnt lgkmcnt(0)
	v_mfma_f32_16x16x32_bf16 v[36:39], v[8:11], v[44:47], 0
	ds_read_b128 v[4:7], v209 offset:43520
	ds_read_b128 v[8:11], v212
	v_mfma_f32_16x16x32_bf16 v[72:75], v[72:75], v[48:51], v[88:91]
	v_mfma_f32_16x16x32_bf16 v[76:79], v[76:79], v[48:51], v[92:95]
	s_waitcnt lgkmcnt(1)
	v_mfma_f32_16x16x32_bf16 v[88:91], v[4:7], v[44:47], 0
	s_waitcnt lgkmcnt(0)
	v_mfma_f32_16x16x32_bf16 v[92:95], v[8:11], v[44:47], 0
	ds_read_b128 v[4:7], v209 offset:47872
	ds_read_b128 v[8:11], v213
	v_mfma_f32_16x16x32_bf16 v[64:67], v[64:67], v[48:51], v[84:87]
	v_mfma_f32_16x16x32_bf16 v[48:51], v[80:83], v[48:51], v[232:235]
	s_waitcnt lgkmcnt(1)
	v_mfma_f32_16x16x32_bf16 v[232:235], v[4:7], v[44:47], 0
	s_waitcnt lgkmcnt(0)
	v_mfma_f32_16x16x32_bf16 v[236:239], v[8:11], v[44:47], 0
	ds_read_b128 v[4:7], v209 offset:52224
	ds_read_b128 v[8:11], v214
	s_waitcnt lgkmcnt(1)
	v_mfma_f32_16x16x32_bf16 v[240:243], v[4:7], v[44:47], 0
	s_waitcnt lgkmcnt(0)
	v_mfma_f32_16x16x32_bf16 v[244:247], v[8:11], v[44:47], 0
	ds_read_b128 v[4:7], v209 offset:56576
	ds_read_b128 v[8:11], v215
	s_waitcnt lgkmcnt(1)
	v_mfma_f32_16x16x32_bf16 v[80:83], v[4:7], v[44:47], 0
	s_waitcnt lgkmcnt(0)
	v_mfma_f32_16x16x32_bf16 v[84:87], v[8:11], v[44:47], 0
	ds_read_b128 v[4:7], v209 offset:60928
	ds_read_b128 v[8:11], v216
	s_waitcnt lgkmcnt(1)
	v_mfma_f32_16x16x32_bf16 v[20:23], v[4:7], v[44:47], 0
	ds_read_b128 v[4:7], v209 offset:65280
	ds_read_b128 v[248:251], v217
	s_waitcnt lgkmcnt(2)
	v_mfma_f32_16x16x32_bf16 v[24:27], v[8:11], v[44:47], 0
	s_waitcnt lgkmcnt(1)
	v_mfma_f32_16x16x32_bf16 v[8:11], v[4:7], v[44:47], 0
	s_waitcnt lgkmcnt(0)
	v_mfma_f32_16x16x32_bf16 v[4:7], v[248:251], v[44:47], 0
	ds_read_b128 v[44:47], v209 offset:34880
	ds_read_b128 v[248:251], v210 offset:64
	s_waitcnt lgkmcnt(1)
	v_mfma_f32_16x16x32_bf16 v[12:15], v[44:47], v[40:43], v[12:15]
	s_waitcnt lgkmcnt(0)
	v_mfma_f32_16x16x32_bf16 v[16:19], v[248:251], v[40:43], v[16:19]
	ds_read_b128 v[44:47], v209 offset:39232
	ds_read_b128 v[248:251], v211 offset:64
	s_waitcnt lgkmcnt(1)
	v_mfma_f32_16x16x32_bf16 v[32:35], v[44:47], v[40:43], v[32:35]
	s_waitcnt lgkmcnt(0)
	v_mfma_f32_16x16x32_bf16 v[36:39], v[248:251], v[40:43], v[36:39]
	ds_read_b128 v[44:47], v209 offset:43584
	ds_read_b128 v[248:251], v212 offset:64
	s_waitcnt lgkmcnt(1)
	v_mfma_f32_16x16x32_bf16 v[44:47], v[44:47], v[40:43], v[88:91]
	s_waitcnt lgkmcnt(0)
	v_mfma_f32_16x16x32_bf16 v[88:91], v[248:251], v[40:43], v[92:95]
	s_nop 2
	ds_read_b128 v[92:95], v209 offset:47936
	ds_read_b128 v[248:251], v213 offset:64
	s_waitcnt lgkmcnt(1)
	v_mfma_f32_16x16x32_bf16 v[92:95], v[92:95], v[40:43], v[232:235]
	s_waitcnt lgkmcnt(0)
	v_mfma_f32_16x16x32_bf16 v[232:235], v[248:251], v[40:43], v[236:239]
	s_nop 2
	ds_read_b128 v[236:239], v209 offset:52288
	ds_read_b128 v[248:251], v214 offset:64
	s_waitcnt lgkmcnt(1)
	v_mfma_f32_16x16x32_bf16 v[236:239], v[236:239], v[40:43], v[240:243]
	s_waitcnt lgkmcnt(0)
	v_mfma_f32_16x16x32_bf16 v[240:243], v[248:251], v[40:43], v[244:247]
	s_nop 2
	ds_read_b128 v[244:247], v209 offset:56640
	ds_read_b128 v[248:251], v215 offset:64
	s_waitcnt lgkmcnt(1)
	v_mfma_f32_16x16x32_bf16 v[80:83], v[244:247], v[40:43], v[80:83]
	s_waitcnt lgkmcnt(0)
	v_mfma_f32_16x16x32_bf16 v[84:87], v[248:251], v[40:43], v[84:87]
	ds_read_b128 v[244:247], v209 offset:60992
	ds_read_b128 v[248:251], v216 offset:64
	s_waitcnt lgkmcnt(1)
	v_mfma_f32_16x16x32_bf16 v[244:247], v[244:247], v[40:43], v[20:23]
	s_waitcnt lgkmcnt(0)
	v_mfma_f32_16x16x32_bf16 v[248:251], v[248:251], v[40:43], v[24:27]
	s_nop 0
	ds_read_b128 v[20:23], v209 offset:65344
	s_nop 0
	ds_read_b128 v[24:27], v217 offset:64
	s_waitcnt lgkmcnt(1)
	v_mfma_f32_16x16x32_bf16 v[8:11], v[20:23], v[40:43], v[8:11]
	s_waitcnt lgkmcnt(0)
	v_mfma_f32_16x16x32_bf16 v[4:7], v[24:27], v[40:43], v[4:7]
	ds_read_b128 v[20:23], v209 offset:34944
	ds_read_b128 v[24:27], v210 offset:128
	s_waitcnt lgkmcnt(1)
	v_mfma_f32_16x16x32_bf16 v[40:43], v[20:23], v[28:31], v[12:15]
	s_waitcnt lgkmcnt(0)
	v_mfma_f32_16x16x32_bf16 v[130:133], v[24:27], v[28:31], v[16:19]
	s_nop 0
	ds_read_b128 v[12:15], v209 offset:39296
	s_nop 0
	ds_read_b128 v[16:19], v211 offset:128
	s_waitcnt lgkmcnt(1)
	v_mfma_f32_16x16x32_bf16 v[32:35], v[12:15], v[28:31], v[32:35]
	s_waitcnt lgkmcnt(0)
	v_mfma_f32_16x16x32_bf16 v[36:39], v[16:19], v[28:31], v[36:39]
	ds_read_b128 v[12:15], v209 offset:43648
	ds_read_b128 v[16:19], v212 offset:128
	s_waitcnt lgkmcnt(1)
	v_mfma_f32_16x16x32_bf16 v[44:47], v[12:15], v[28:31], v[44:47]
	s_waitcnt lgkmcnt(0)
	v_mfma_f32_16x16x32_bf16 v[88:91], v[16:19], v[28:31], v[88:91]
	ds_read_b128 v[12:15], v209 offset:48000
	ds_read_b128 v[16:19], v213 offset:128
	s_waitcnt lgkmcnt(1)
	v_mfma_f32_16x16x32_bf16 v[92:95], v[12:15], v[28:31], v[92:95]
	s_waitcnt lgkmcnt(0)
	v_mfma_f32_16x16x32_bf16 v[232:235], v[16:19], v[28:31], v[232:235]
	ds_read_b128 v[12:15], v209 offset:52352
	ds_read_b128 v[16:19], v214 offset:128
	s_waitcnt lgkmcnt(1)
	v_mfma_f32_16x16x32_bf16 v[236:239], v[12:15], v[28:31], v[236:239]
	s_waitcnt lgkmcnt(0)
	v_mfma_f32_16x16x32_bf16 v[240:243], v[16:19], v[28:31], v[240:243]
	ds_read_b128 v[12:15], v209 offset:56704
	ds_read_b128 v[16:19], v215 offset:128
	s_waitcnt lgkmcnt(1)
; #define LAS __attribute__((address_space(3)))
; __device__ __forceinline__ float fexp2(float x) { return __builtin_amdgcn_exp2f(x); }
; #define MFMA16(a, b, c) __builtin_amdgcn_mfma_f32_16x16x32_bf16((a), (b), (c), 0, 0, 0)
; __device__ __forceinline__ void ret_unit(LAS unsigned char* lds, int u, const bf16* PROJ, const int* pos, const float* dec_f, const float* dec_b, const bf16* ST,
;                                          const float* gn_w, const float* gn_b, bf16* MIX, int tid, const WsRef& wsr) {
;     ...
;         for (int kk = 0; kk < 4; ++kk)
; #pragma unroll
;             for (int n = 0; n < 8; ++n) { const bf16x8 yf = *(const LAS bf16x8*)(Ks + (n * 16 + fr) * LDT + kk * 32 + fq * 8); const bf16x8 yb = *(const LAS bf16x8*)(VT + (n * 16 + fr) * LDT + kk * 32 + fq * 8);
;                 tf[n] = MFMA16(yf, qf[kk], tf[n]); tb[n] = MFMA16(yb, qf[kk], tb[n]); }
;         const float xif = fexp2(lgf2 * (float)(q + 1)), xib = fexp2(lgb2 * (float)(128 - q));
; #pragma unroll
;         for (int n = 0; n < 8; ++n) o[n] = o[n] + tf[n] * xif + tb[n] * xib;
;     }
;     float sm = 0.f;
; #pragma unroll
;     for (int n = 0; n < 8; ++n) sm += (o[n][0] + o[n][1]) + (o[n][2] + o[n][3]);
;     sm += __shfl_xor(sm, 16); sm += __shfl_xor(sm, 32);
;     const float mu = sm * (1.f / 128.f);
;     float vq = 0.f;
; #pragma unroll
;     for (int n = 0; n < 8; ++n) { const f32x4 d = o[n] - mu; vq += (d[0] * d[0] + d[1] * d[1]) + (d[2] * d[2] + d[3] * d[3]); }
;     vq += __shfl_xor(vq, 16); vq += __shfl_xor(vq, 32);
	v_mfma_f32_16x16x32_bf16 v[20:23], v[12:15], v[28:31], v[80:83]
	s_waitcnt lgkmcnt(0)
	v_mfma_f32_16x16x32_bf16 v[24:27], v[16:19], v[28:31], v[84:87]
	ds_read_b128 v[12:15], v209 offset:61056
	ds_read_b128 v[16:19], v216 offset:128
	ds_read_b128 v[80:83], v209 offset:65408
	ds_read_b128 v[84:87], v217 offset:128
	s_waitcnt lgkmcnt(3)
	v_mfma_f32_16x16x32_bf16 v[12:15], v[12:15], v[28:31], v[244:247]
	s_waitcnt lgkmcnt(2)
	v_mfma_f32_16x16x32_bf16 v[16:19], v[16:19], v[28:31], v[248:251]
	s_waitcnt lgkmcnt(1)
	v_mfma_f32_16x16x32_bf16 v[8:11], v[80:83], v[28:31], v[8:11]
	s_waitcnt lgkmcnt(0)
	v_mfma_f32_16x16x32_bf16 v[4:7], v[84:87], v[28:31], v[4:7]
	ds_read_b128 v[28:31], v209 offset:35008
	ds_read_b128 v[80:83], v210 offset:192
	s_waitcnt lgkmcnt(1)
	v_mfma_f32_16x16x32_bf16 v[28:31], v[28:31], v[0:3], v[40:43]
	s_waitcnt lgkmcnt(0)
	v_mfma_f32_16x16x32_bf16 v[40:43], v[80:83], v[0:3], v[130:133]
	ds_read_b128 v[80:83], v209 offset:39360
	ds_read_b128 v[84:87], v211 offset:192
	s_waitcnt lgkmcnt(1)
	v_mfma_f32_16x16x32_bf16 v[80:83], v[80:83], v[0:3], v[32:35]
	s_waitcnt lgkmcnt(0)
	v_mfma_f32_16x16x32_bf16 v[34:37], v[84:87], v[0:3], v[36:39]
	ds_read_b128 v[84:87], v209 offset:43712
	ds_read_b128 v[130:133], v212 offset:192
	s_waitcnt lgkmcnt(1)
	v_mfma_f32_16x16x32_bf16 v[44:47], v[84:87], v[0:3], v[44:47]
	s_waitcnt lgkmcnt(0)
	v_mfma_f32_16x16x32_bf16 v[84:87], v[130:133], v[0:3], v[88:91]
	s_nop 2
	ds_read_b128 v[88:91], v209 offset:48064
	ds_read_b128 v[130:133], v213 offset:192
	s_waitcnt lgkmcnt(1)
	v_mfma_f32_16x16x32_bf16 v[88:91], v[88:91], v[0:3], v[92:95]
	s_waitcnt lgkmcnt(0)
	v_mfma_f32_16x16x32_bf16 v[92:95], v[130:133], v[0:3], v[232:235]
	ds_read_b128 v[130:133], v209 offset:52416
	s_nop 1
	ds_read_b128 v[232:235], v214 offset:192
	s_waitcnt lgkmcnt(1)
	v_mfma_f32_16x16x32_bf16 v[130:133], v[130:133], v[0:3], v[236:239]
	s_waitcnt lgkmcnt(0)
	v_mfma_f32_16x16x32_bf16 v[232:235], v[232:235], v[0:3], v[240:243]
	s_nop 0
	ds_read_b128 v[236:239], v209 offset:56768
	s_nop 0
	ds_read_b128 v[240:243], v215 offset:192
	s_waitcnt lgkmcnt(1)
	v_mfma_f32_16x16x32_bf16 v[236:239], v[236:239], v[0:3], v[20:23]
	s_waitcnt lgkmcnt(0)
	v_mfma_f32_16x16x32_bf16 v[240:243], v[240:243], v[0:3], v[24:27]
	s_nop 0
	ds_read_b128 v[20:23], v209 offset:61120
	s_nop 0
	ds_read_b128 v[24:27], v216 offset:192
	s_waitcnt lgkmcnt(1)
	v_mfma_f32_16x16x32_bf16 v[12:15], v[20:23], v[0:3], v[12:15]
	s_waitcnt lgkmcnt(0)
	v_mfma_f32_16x16x32_bf16 v[244:247], v[24:27], v[0:3], v[16:19]
	s_nop 2
	ds_read_b128 v[16:19], v209 offset:65472
	ds_read_b128 v[20:23], v217 offset:192
	s_waitcnt lgkmcnt(1)
	v_mfma_f32_16x16x32_bf16 v[8:11], v[16:19], v[0:3], v[8:11]
	s_waitcnt lgkmcnt(0)
	v_mfma_f32_16x16x32_bf16 v[248:251], v[20:23], v[0:3], v[4:7]
	v_mul_f32_e32 v0, v105, v218
	v_exp_f32_e32 v38, v0
	v_mul_f32_e32 v0, v230, v219
	v_exp_f32_e32 v230, v0
	v_pk_fma_f32 v[2:3], v[38:39], v[28:29], v[52:53] op_sel_hi:[0,1,1]
	v_pk_fma_f32 v[16:17], v[38:39], v[132:133], v[70:71] op_sel_hi:[0,1,1]
	v_pk_fma_f32 v[0:1], v[38:39], v[30:31], v[54:55] op_sel_hi:[0,1,1]
	v_pk_fma_f32 v[32:33], v[230:231], v[40:41], v[2:3] op_sel_hi:[0,1,1]
	v_pk_fma_f32 v[2:3], v[38:39], v[80:81], v[56:57] op_sel_hi:[0,1,1]
	v_pk_fma_f32 v[18:19], v[38:39], v[130:131], v[68:69] op_sel_hi:[0,1,1]
	v_pk_fma_f32 v[22:23], v[230:231], v[234:235], v[16:17] op_sel_hi:[0,1,1]
	v_pk_fma_f32 v[16:17], v[38:39], v[238:239], v[74:75] op_sel_hi:[0,1,1]
	v_pk_fma_f32 v[12:13], v[38:39], v[12:13], v[76:77] op_sel_hi:[0,1,1]
	v_pk_fma_f32 v[30:31], v[230:231], v[42:43], v[0:1] op_sel_hi:[0,1,1]
	v_pk_fma_f32 v[0:1], v[38:39], v[82:83], v[58:59] op_sel_hi:[0,1,1]
	v_pk_fma_f32 v[28:29], v[230:231], v[34:35], v[2:3] op_sel_hi:[0,1,1]
	v_pk_fma_f32 v[24:25], v[230:231], v[232:233], v[18:19] op_sel_hi:[0,1,1]
	v_pk_fma_f32 v[18:19], v[230:231], v[242:243], v[16:17] op_sel_hi:[0,1,1]
	v_pk_fma_f32 v[16:17], v[230:231], v[244:245], v[12:13] op_sel_hi:[0,1,1]
	v_pk_fma_f32 v[10:11], v[38:39], v[10:11], v[50:51] op_sel_hi:[0,1,1]
	v_pk_fma_f32 v[12:13], v[38:39], v[8:9], v[48:49] op_sel_hi:[0,1,1]
	v_pk_fma_f32 v[26:27], v[230:231], v[36:37], v[0:1] op_sel_hi:[0,1,1]
	v_pk_fma_f32 v[8:9], v[230:231], v[250:251], v[10:11] op_sel_hi:[0,1,1]
	v_pk_fma_f32 v[10:11], v[230:231], v[248:249], v[12:13] op_sel_hi:[0,1,1]
	v_mov_b32_e32 v12, v32
	v_mov_b32_e32 v13, v28
	v_mov_b32_e32 v34, v33
	v_mov_b32_e32 v35, v29
	v_pk_fma_f32 v[0:1], v[38:39], v[46:47], v[62:63] op_sel_hi:[0,1,1]
	v_pk_fma_f32 v[2:3], v[38:39], v[44:45], v[60:61] op_sel_hi:[0,1,1]
	v_pk_add_f32 v[12:13], v[12:13], v[34:35]
	v_mov_b32_e32 v34, v30
	v_mov_b32_e32 v35, v26
	v_mov_b32_e32 v36, v31
	v_mov_b32_e32 v37, v27
	v_pk_fma_f32 v[4:5], v[230:231], v[86:87], v[0:1] op_sel_hi:[0,1,1]
	v_pk_fma_f32 v[6:7], v[230:231], v[84:85], v[2:3] op_sel_hi:[0,1,1]
	v_pk_add_f32 v[34:35], v[34:35], v[36:37]
	v_mov_b32_e32 v36, v6
	v_pk_add_f32 v[12:13], v[12:13], v[34:35]
	v_pk_mov_b32 v[34:35], v[6:7], v[4:5] op_sel:[1,0]
	v_mov_b32_e32 v37, v5
	v_pk_fma_f32 v[0:1], v[38:39], v[90:91], v[66:67] op_sel_hi:[0,1,1]
	v_pk_fma_f32 v[2:3], v[38:39], v[88:89], v[64:65] op_sel_hi:[0,1,1]
	v_pk_add_f32 v[34:35], v[34:35], v[36:37]
	v_pk_fma_f32 v[0:1], v[230:231], v[94:95], v[0:1] op_sel_hi:[0,1,1]
	v_pk_fma_f32 v[2:3], v[230:231], v[92:93], v[2:3] op_sel_hi:[0,1,1]
	v_add_f32_e32 v12, 0, v12
	v_pk_add_f32 v[34:35], v[34:35], v[34:35] op_sel:[0,1] op_sel_hi:[1,0]
	v_pk_fma_f32 v[20:21], v[38:39], v[236:237], v[72:73] op_sel_hi:[0,1,1]
	v_pk_fma_f32 v[14:15], v[38:39], v[14:15], v[78:79] op_sel_hi:[0,1,1]
	v_add_f32_e32 v12, v12, v13
	v_add_f32_e32 v36, v2, v3
	v_add_f32_e32 v38, v0, v1
	v_mov_b32_e32 v13, v24
	v_mov_b32_e32 v35, v25
	v_mov_b32_e32 v37, v22
	v_mov_b32_e32 v39, v23
	v_pk_fma_f32 v[20:21], v[230:231], v[240:241], v[20:21] op_sel_hi:[0,1,1]
	v_pk_add_f32 v[12:13], v[12:13], v[34:35]
	v_pk_add_f32 v[34:35], v[36:37], v[38:39]
	v_mov_b32_e32 v36, v20
	v_pk_add_f32 v[12:13], v[12:13], v[34:35]
	v_pk_mov_b32 v[34:35], v[20:21], v[18:19] op_sel:[1,0]
	v_mov_b32_e32 v37, v19
	v_pk_add_f32 v[34:35], v[34:35], v[36:37]
	v_pk_fma_f32 v[14:15], v[230:231], v[246:247], v[14:15] op_sel_hi:[0,1,1]
	v_pk_add_f32 v[12:13], v[12:13], v[12:13] op_sel:[0,1] op_sel_hi:[1,0]
	v_pk_add_f32 v[34:35], v[34:35], v[34:35] op_sel:[0,1] op_sel_hi:[1,0]
	v_add_f32_e32 v36, v16, v17
	v_add_f32_e32 v38, v14, v15
	v_mov_b32_e32 v13, v10
	v_mov_b32_e32 v35, v11
	v_mov_b32_e32 v37, v8
	v_mov_b32_e32 v39, v9
	v_pk_add_f32 v[12:13], v[12:13], v[34:35]
	v_pk_add_f32 v[34:35], v[36:37], v[38:39]
	v_or_b32_e32 v48, s0, v126
	v_pk_add_f32 v[12:13], v[12:13], v[34:35]
	v_mov_b32_e32 v49, v97
	v_add_f32_e32 v12, v12, v13
	ds_bpermute_b32 v13, v220, v12
	s_waitcnt lgkmcnt(0)
; __device__ __forceinline__ float bflo(unsigned w) { return __uint_as_float(w << 16); }
; __device__ __forceinline__ float bfhi(unsigned w) { return __uint_as_float(w & 0xffff0000u); }
; __device__ __forceinline__ void ret_unit(LAS unsigned char* lds, int u, const bf16* PROJ, const int* pos, const float* dec_f, const float* dec_b, const bf16* ST,
;                                          const float* gn_w, const float* gn_b, bf16* MIX, int tid, const WsRef& wsr) {
;     ...
;     float sm = 0.f;
; #pragma unroll
;     for (int n = 0; n < 8; ++n) sm += (o[n][0] + o[n][1]) + (o[n][2] + o[n][3]);
;     sm += __shfl_xor(sm, 16); sm += __shfl_xor(sm, 32);
;     const float mu = sm * (1.f / 128.f);
;     float vq = 0.f;
; #pragma unroll
;     for (int n = 0; n < 8; ++n) { const f32x4 d = o[n] - mu; vq += (d[0] * d[0] + d[1] * d[1]) + (d[2] * d[2] + d[3] * d[3]); }
;     vq += __shfl_xor(vq, 16); vq += __shfl_xor(vq, 32);
;     const float rstd = rsqrtf(vq * (1.f / 128.f) + EPS);
;     const size_t row = row0 + q;
; #pragma unroll
;     for (int n = 0; n < 8; ++n) { const int col = h * 128 + n * 16 + 4 * fq;
;         const f32x4 gw = *(const f32x4*)(gn_w + col), gb = *(const f32x4*)(gn_b + col);
;         const u32x2 gg = *(const u32x2*)(PROJ + row * INC + 1536 + col);
;         const f32x4 g = (f32x4){bflo(gg.x), bfhi(gg.x), bflo(gg.y), bfhi(gg.y)};
;         f32x4 y = (o[n] - mu) * rstd * gw + gb;
	v_add_f32_e32 v12, v12, v13
	ds_bpermute_b32 v13, v221, v12
	s_waitcnt lgkmcnt(0)
	v_add_f32_e32 v40, v12, v13
	v_fmamk_f32 v33, v40, 0xbc000000, v33
	v_fmamk_f32 v29, v40, 0xbc000000, v29
	v_fmamk_f32 v31, v40, 0xbc000000, v31
	v_fmac_f32_e32 v32, 0xbc000000, v40
	v_fmamk_f32 v27, v40, 0xbc000000, v27
	v_fmac_f32_e32 v28, 0xbc000000, v40
	v_mov_b32_e32 v34, v33
	v_mov_b32_e32 v35, v29
	v_fmac_f32_e32 v30, 0xbc000000, v40
	v_fmac_f32_e32 v26, 0xbc000000, v40
	v_mov_b32_e32 v12, v32
	v_mov_b32_e32 v13, v28
	v_pk_mul_f32 v[34:35], v[34:35], v[34:35]
	v_mov_b32_e32 v36, v31
	v_mov_b32_e32 v37, v27
	v_pk_fma_f32 v[12:13], v[12:13], v[12:13], v[34:35]
	v_mov_b32_e32 v34, v30
	v_mov_b32_e32 v35, v26
	v_pk_mul_f32 v[36:37], v[36:37], v[36:37]
	v_fmamk_f32 v7, v40, 0xbc000000, v7
	v_pk_fma_f32 v[34:35], v[34:35], v[34:35], v[36:37]
	v_fmac_f32_e32 v6, 0xbc000000, v40
	v_pk_add_f32 v[12:13], v[12:13], v[34:35]
	v_fmamk_f32 v5, v40, 0xbc000000, v5
	v_fmac_f32_e32 v4, 0xbc000000, v40
	v_pk_add_f32 v[12:13], v[12:13], v[12:13] op_sel_hi:[0,1]
	v_pk_mul_f32 v[34:35], v[4:5], v[4:5]
	v_pk_mul_f32 v[36:37], v[6:7], v[6:7]
	v_fmac_f32_e32 v2, 0xbc000000, v40
	v_pk_mov_b32 v[38:39], v[36:37], v[34:35] op_sel:[1,0]
	v_mov_b32_e32 v37, v35
	v_fmamk_f32 v3, v40, 0xbc000000, v3
	v_fmac_f32_e32 v0, 0xbc000000, v40
	v_mul_f32_e32 v12, v2, v2
	v_pk_add_f32 v[34:35], v[38:39], v[36:37]
	v_fmamk_f32 v1, v40, 0xbc000000, v1
	v_pk_fma_f32 v[36:37], v[2:3], v[2:3], v[12:13] op_sel_hi:[1,1,0]
	v_mul_f32_e32 v12, v0, v0
	v_pk_add_f32 v[34:35], v[34:35], v[34:35] op_sel_hi:[0,1]
	v_pk_fma_f32 v[38:39], v[0:1], v[0:1], v[12:13] op_sel_hi:[1,1,0]
	v_fmamk_f32 v23, v40, 0xbc000000, v23
	v_fmac_f32_e32 v22, 0xbc000000, v40
	v_fmamk_f32 v25, v40, 0xbc000000, v25
	v_fmac_f32_e32 v24, 0xbc000000, v40
	v_mul_f32_e32 v36, v24, v24
	v_mul_f32_e32 v38, v25, v25
	v_mul_f32_e32 v34, v22, v22
	v_mul_f32_e32 v12, v23, v23
	v_pk_add_f32 v[36:37], v[36:37], v[38:39]
	v_pk_add_f32 v[12:13], v[34:35], v[12:13]
	v_fmamk_f32 v21, v40, 0xbc000000, v21
	v_pk_add_f32 v[12:13], v[36:37], v[12:13]
	v_fmac_f32_e32 v20, 0xbc000000, v40
	v_fmamk_f32 v19, v40, 0xbc000000, v19
	v_fmac_f32_e32 v18, 0xbc000000, v40
	v_pk_add_f32 v[12:13], v[12:13], v[12:13] op_sel_hi:[0,1]
	v_pk_mul_f32 v[34:35], v[18:19], v[18:19]
	v_pk_mul_f32 v[36:37], v[20:21], v[20:21]
	v_fmac_f32_e32 v16, 0xbc000000, v40
	v_pk_mov_b32 v[38:39], v[36:37], v[34:35] op_sel:[1,0]
	v_mov_b32_e32 v37, v35
	v_fmamk_f32 v17, v40, 0xbc000000, v17
	v_fmac_f32_e32 v14, 0xbc000000, v40
	v_mul_f32_e32 v12, v16, v16
	v_pk_add_f32 v[34:35], v[38:39], v[36:37]
	v_fmamk_f32 v15, v40, 0xbc000000, v15
	v_pk_fma_f32 v[36:37], v[16:17], v[16:17], v[12:13] op_sel_hi:[1,1,0]
	v_mul_f32_e32 v12, v14, v14
	v_pk_add_f32 v[34:35], v[34:35], v[34:35] op_sel_hi:[0,1]
	v_pk_fma_f32 v[38:39], v[14:15], v[14:15], v[12:13] op_sel_hi:[1,1,0]
	v_fmamk_f32 v9, v40, 0xbc000000, v9
	v_fmac_f32_e32 v8, 0xbc000000, v40
	v_fmamk_f32 v11, v40, 0xbc000000, v11
	v_fmac_f32_e32 v10, 0xbc000000, v40
	v_mul_f32_e32 v36, v10, v10
	v_mul_f32_e32 v38, v11, v11
	v_mul_f32_e32 v34, v8, v8
	v_mul_f32_e32 v12, v9, v9
	v_pk_add_f32 v[36:37], v[36:37], v[38:39]
	v_pk_add_f32 v[12:13], v[34:35], v[12:13]
	v_lshl_add_u64 v[34:35], s[4:5], 0, v[102:103]
	v_pk_add_f32 v[12:13], v[36:37], v[12:13]
	v_mov_b64_e32 v[36:37], s[6:7]
	v_add_f32_e32 v12, v12, v13
	ds_bpermute_b32 v13, v220, v12
	s_waitcnt lgkmcnt(0)
	v_add_f32_e32 v12, v12, v13
	ds_bpermute_b32 v13, v221, v12
	s_waitcnt lgkmcnt(0)
	v_add_f32_e32 v12, v12, v13
	v_fmamk_f32 v12, v12, 0x3c000000, v227
	v_cmp_gt_f32_e64 s[68:69], s1, v12
	v_mul_f32_e32 v13, 0x4b800000, v12
	v_mad_u64_u32 v[44:45], s[0:1], v34, s72, v[36:37]
	v_cndmask_b32_e64 v12, v12, v13, s[68:69]
	v_rsq_f32_e32 v12, v12
	v_mad_i32_i24 v45, v35, s72, v45
	v_lshlrev_b64 v[34:35], 11, v[34:35]
	v_lshl_add_u64 v[46:47], s[70:71], 0, v[34:35]
	v_mul_f32_e32 v13, 0x45800000, v12
	v_cndmask_b32_e64 v12, v12, v13, s[68:69]
	v_lshlrev_b32_e32 v13, 2, v48
	v_lshlrev_b32_e32 v48, 1, v48
	v_lshl_add_u64 v[34:35], v[44:45], 0, v[48:49]
	v_lshl_add_u64 v[46:47], v[46:47], 0, v[48:49]
	global_load_dwordx2 v[56:57], v[34:35], off offset:3072
	global_load_dwordx2 v[58:59], v[34:35], off offset:3104
	global_load_dwordx2 v[60:61], v[34:35], off offset:3136
	global_load_dwordx2 v[62:63], v[34:35], off offset:3168
	global_load_dwordx2 v[64:65], v[34:35], off offset:3200
	global_load_dwordx2 v[66:67], v[34:35], off offset:3232
	global_load_dwordx2 v[68:69], v[34:35], off offset:3264
	global_load_dwordx2 v[70:71], v[34:35], off offset:3296
	global_load_dwordx4 v[72:75], v13, s[22:23]
	global_load_dwordx4 v[76:79], v13, s[36:37]
	global_load_dwordx4 v[80:83], v13, s[22:23] offset:64
	global_load_dwordx4 v[84:87], v13, s[36:37] offset:64
	global_load_dwordx4 v[88:91], v13, s[22:23] offset:128
	global_load_dwordx4 v[92:95], v13, s[36:37] offset:128
	global_load_dwordx4 v[36:39], v13, s[22:23] offset:192
	global_load_dwordx4 v[40:43], v13, s[36:37] offset:192
	global_load_dwordx4 v[232:235], v13, s[22:23] offset:256
	global_load_dwordx4 v[236:239], v13, s[36:37] offset:256
	global_load_dwordx4 v[240:243], v13, s[22:23] offset:320
	global_load_dwordx4 v[248:251], v13, s[36:37] offset:320
	v_pk_mul_f32 v[32:33], v[32:33], v[12:13] op_sel_hi:[1,0]
	v_pk_mul_f32 v[30:31], v[30:31], v[12:13] op_sel_hi:[1,0]
	v_pk_mul_f32 v[28:29], v[28:29], v[12:13] op_sel_hi:[1,0]
	v_pk_mul_f32 v[26:27], v[26:27], v[12:13] op_sel_hi:[1,0]
	v_pk_mul_f32 v[6:7], v[6:7], v[12:13] op_sel_hi:[1,0]
	v_pk_mul_f32 v[4:5], v[4:5], v[12:13] op_sel_hi:[1,0]
	v_pk_mul_f32 v[2:3], v[2:3], v[12:13] op_sel_hi:[1,0]
	v_pk_mul_f32 v[0:1], v[0:1], v[12:13] op_sel_hi:[1,0]
	v_pk_mul_f32 v[24:25], v[24:25], v[12:13] op_sel_hi:[1,0]
	v_pk_mul_f32 v[22:23], v[22:23], v[12:13] op_sel_hi:[1,0]
	v_pk_mul_f32 v[20:21], v[20:21], v[12:13] op_sel_hi:[1,0]
	v_pk_mul_f32 v[18:19], v[18:19], v[12:13] op_sel_hi:[1,0]
	v_pk_mul_f32 v[16:17], v[16:17], v[12:13] op_sel_hi:[1,0]
	v_pk_mul_f32 v[14:15], v[14:15], v[12:13] op_sel_hi:[1,0]
	v_pk_mul_f32 v[10:11], v[10:11], v[12:13] op_sel_hi:[1,0]
	v_pk_mul_f32 v[8:9], v[8:9], v[12:13] op_sel_hi:[1,0]
	s_waitcnt vmcnt(10)
; __device__ __forceinline__ unsigned pk2(float lo, float hi) { return pg8::cvt_pk_bf16(lo, hi); }
; __device__ __forceinline__ float bflo(unsigned w) { return __uint_as_float(w << 16); }
; __device__ __forceinline__ float bfhi(unsigned w) { return __uint_as_float(w & 0xffff0000u); }
; __device__ __forceinline__ void ret_unit(LAS unsigned char* lds, int u, const bf16* PROJ, const int* pos, const float* dec_f, const float* dec_b, const bf16* ST,
;                                          const float* gn_w, const float* gn_b, bf16* MIX, int tid, const WsRef& wsr) {
;     ...
;     for (int n = 0; n < 8; ++n) { const int col = h * 128 + n * 16 + 4 * fq;
;         const f32x4 gw = *(const f32x4*)(gn_w + col), gb = *(const f32x4*)(gn_b + col);
;         const u32x2 gg = *(const u32x2*)(PROJ + row * INC + 1536 + col);
;         const f32x4 g = (f32x4){bflo(gg.x), bfhi(gg.x), bflo(gg.y), bfhi(gg.y)};
;         f32x4 y = (o[n] - mu) * rstd * gw + gb;
; #pragma unroll
;         for (int r = 0; r < 4; ++r) y[r] = y[r] * g[r] * __builtin_amdgcn_rcpf(1.f + __expf(-g[r]));
;         u32x2 w; w.x = pk2(y[0], y[1]); w.y = pk2(y[2], y[3]); *(u32x2*)(MIX + row * D + col) = w; }
	v_lshlrev_b32_e32 v130, 16, v56
	v_and_b32_e32 v131, 0xffff0000, v56
	v_lshlrev_b32_e32 v132, 16, v57
	v_and_b32_e32 v133, 0xffff0000, v57
	v_pk_fma_f32 v[32:33], v[72:73], v[32:33], v[76:77]
	v_pk_fma_f32 v[30:31], v[74:75], v[30:31], v[78:79]
	global_load_dwordx4 v[72:75], v13, s[22:23] offset:384
	global_load_dwordx4 v[76:79], v13, s[36:37] offset:384
	v_mul_f32_e32 v56, 0xbfb8aa3b, v130
	v_mul_f32_e32 v57, 0xbfb8aa3b, v131
	v_exp_f32_e32 v56, v56
	v_exp_f32_e32 v57, v57
	v_pk_mul_f32 v[32:33], v[32:33], v[130:131]
	v_mul_f32_e32 v130, 0xbfb8aa3b, v132
	v_mul_f32_e32 v131, 0xbfb8aa3b, v133
	v_add_f32_e32 v56, 1.0, v56
	v_add_f32_e32 v57, 1.0, v57
	v_rcp_f32_e32 v56, v56
	v_rcp_f32_e32 v57, v57
	v_exp_f32_e32 v130, v130
	v_exp_f32_e32 v131, v131
	v_pk_mul_f32 v[30:31], v[30:31], v[132:133]
	v_pk_mul_f32 v[32:33], v[56:57], v[32:33]
	v_add_f32_e32 v130, 1.0, v130
	v_add_f32_e32 v131, 1.0, v131
	v_rcp_f32_e32 v130, v130
	v_rcp_f32_e32 v131, v131
	v_cvt_pk_bf16_f32 v56, v32, v33
	s_nop 0
	v_pk_mul_f32 v[30:31], v[130:131], v[30:31]
	s_nop 0
	v_cvt_pk_bf16_f32 v57, v30, v31
	global_store_dwordx2 v[46:47], v[56:57], off
	s_waitcnt vmcnt(11)
	v_lshlrev_b32_e32 v130, 16, v58
	v_and_b32_e32 v131, 0xffff0000, v58
	v_lshlrev_b32_e32 v132, 16, v59
	v_and_b32_e32 v133, 0xffff0000, v59
	v_pk_fma_f32 v[28:29], v[80:81], v[28:29], v[84:85]
	v_pk_fma_f32 v[26:27], v[82:83], v[26:27], v[86:87]
	global_load_dwordx4 v[80:83], v13, s[22:23] offset:448
	global_load_dwordx4 v[84:87], v13, s[36:37] offset:448
	v_mul_f32_e32 v58, 0xbfb8aa3b, v130
	v_mul_f32_e32 v59, 0xbfb8aa3b, v131
	v_exp_f32_e32 v58, v58
	v_exp_f32_e32 v59, v59
	v_pk_mul_f32 v[28:29], v[28:29], v[130:131]
	v_mul_f32_e32 v130, 0xbfb8aa3b, v132
	v_mul_f32_e32 v131, 0xbfb8aa3b, v133
	v_add_f32_e32 v58, 1.0, v58
	v_add_f32_e32 v59, 1.0, v59
	v_rcp_f32_e32 v58, v58
	v_rcp_f32_e32 v59, v59
	v_exp_f32_e32 v130, v130
	v_exp_f32_e32 v131, v131
	v_pk_mul_f32 v[26:27], v[26:27], v[132:133]
	v_pk_mul_f32 v[28:29], v[58:59], v[28:29]
	v_add_f32_e32 v130, 1.0, v130
	v_add_f32_e32 v131, 1.0, v131
	v_rcp_f32_e32 v130, v130
	v_rcp_f32_e32 v131, v131
	v_cvt_pk_bf16_f32 v58, v28, v29
	s_nop 0
	v_pk_mul_f32 v[26:27], v[130:131], v[26:27]
	s_nop 0
	v_cvt_pk_bf16_f32 v59, v26, v27
	global_store_dwordx2 v[46:47], v[58:59], off offset:32
	s_waitcnt vmcnt(12)
	v_lshlrev_b32_e32 v130, 16, v60
	v_and_b32_e32 v131, 0xffff0000, v60
	v_lshlrev_b32_e32 v132, 16, v61
	v_and_b32_e32 v133, 0xffff0000, v61
	v_pk_fma_f32 v[6:7], v[88:89], v[6:7], v[92:93]
	v_pk_fma_f32 v[4:5], v[90:91], v[4:5], v[94:95]
	v_mul_f32_e32 v60, 0xbfb8aa3b, v130
	v_mul_f32_e32 v61, 0xbfb8aa3b, v131
	v_exp_f32_e32 v60, v60
	v_exp_f32_e32 v61, v61
	v_pk_mul_f32 v[6:7], v[6:7], v[130:131]
	v_mul_f32_e32 v130, 0xbfb8aa3b, v132
	v_mul_f32_e32 v131, 0xbfb8aa3b, v133
	v_add_f32_e32 v60, 1.0, v60
	v_add_f32_e32 v61, 1.0, v61
	v_rcp_f32_e32 v60, v60
	v_rcp_f32_e32 v61, v61
	v_exp_f32_e32 v130, v130
	v_exp_f32_e32 v131, v131
	v_pk_mul_f32 v[4:5], v[4:5], v[132:133]
	v_pk_mul_f32 v[6:7], v[60:61], v[6:7]
	v_add_f32_e32 v130, 1.0, v130
	v_add_f32_e32 v131, 1.0, v131
	v_rcp_f32_e32 v130, v130
	v_rcp_f32_e32 v131, v131
	v_cvt_pk_bf16_f32 v60, v6, v7
	s_nop 0
	v_pk_mul_f32 v[4:5], v[130:131], v[4:5]
	s_nop 0
	v_cvt_pk_bf16_f32 v61, v4, v5
	global_store_dwordx2 v[46:47], v[60:61], off offset:64
	s_waitcnt vmcnt(11)
	v_lshlrev_b32_e32 v130, 16, v62
	v_and_b32_e32 v131, 0xffff0000, v62
	v_lshlrev_b32_e32 v132, 16, v63
	v_and_b32_e32 v133, 0xffff0000, v63
	v_pk_fma_f32 v[2:3], v[36:37], v[2:3], v[40:41]
	v_pk_fma_f32 v[0:1], v[38:39], v[0:1], v[42:43]
	v_mul_f32_e32 v62, 0xbfb8aa3b, v130
	v_mul_f32_e32 v63, 0xbfb8aa3b, v131
	v_exp_f32_e32 v62, v62
	v_exp_f32_e32 v63, v63
	v_pk_mul_f32 v[2:3], v[2:3], v[130:131]
	v_mul_f32_e32 v130, 0xbfb8aa3b, v132
	v_mul_f32_e32 v131, 0xbfb8aa3b, v133
	v_add_f32_e32 v62, 1.0, v62
	v_add_f32_e32 v63, 1.0, v63
	v_rcp_f32_e32 v62, v62
	v_rcp_f32_e32 v63, v63
	v_exp_f32_e32 v130, v130
	v_exp_f32_e32 v131, v131
	v_pk_mul_f32 v[0:1], v[0:1], v[132:133]
	v_pk_mul_f32 v[2:3], v[62:63], v[2:3]
	v_add_f32_e32 v130, 1.0, v130
	v_add_f32_e32 v131, 1.0, v131
	v_rcp_f32_e32 v130, v130
	v_rcp_f32_e32 v131, v131
	v_cvt_pk_bf16_f32 v62, v2, v3
	s_nop 0
	v_pk_mul_f32 v[0:1], v[130:131], v[0:1]
	s_nop 0
	v_cvt_pk_bf16_f32 v63, v0, v1
	global_store_dwordx2 v[46:47], v[62:63], off offset:96
	s_waitcnt vmcnt(10)
; __device__ __forceinline__ unsigned pk2(float lo, float hi) { return pg8::cvt_pk_bf16(lo, hi); }
; __device__ __forceinline__ float bflo(unsigned w) { return __uint_as_float(w << 16); }
; __device__ __forceinline__ float bfhi(unsigned w) { return __uint_as_float(w & 0xffff0000u); }
; __device__ __forceinline__ void ret_unit(LAS unsigned char* lds, int u, const bf16* PROJ, const int* pos, const float* dec_f, const float* dec_b, const bf16* ST,
;                                          const float* gn_w, const float* gn_b, bf16* MIX, int tid, const WsRef& wsr) {
;     ...
;     for (int n = 0; n < 8; ++n) { const int col = h * 128 + n * 16 + 4 * fq;
;         const f32x4 gw = *(const f32x4*)(gn_w + col), gb = *(const f32x4*)(gn_b + col);
;         const u32x2 gg = *(const u32x2*)(PROJ + row * INC + 1536 + col);
;         const f32x4 g = (f32x4){bflo(gg.x), bfhi(gg.x), bflo(gg.y), bfhi(gg.y)};
;         f32x4 y = (o[n] - mu) * rstd * gw + gb;
; #pragma unroll
;         for (int r = 0; r < 4; ++r) y[r] = y[r] * g[r] * __builtin_amdgcn_rcpf(1.f + __expf(-g[r]));
;         u32x2 w; w.x = pk2(y[0], y[1]); w.y = pk2(y[2], y[3]); *(u32x2*)(MIX + row * D + col) = w; }
;     __syncthreads();
	v_lshlrev_b32_e32 v130, 16, v64
	v_and_b32_e32 v131, 0xffff0000, v64
	v_lshlrev_b32_e32 v132, 16, v65
	v_and_b32_e32 v133, 0xffff0000, v65
	v_pk_fma_f32 v[24:25], v[232:233], v[24:25], v[236:237]
	v_pk_fma_f32 v[22:23], v[234:235], v[22:23], v[238:239]
	v_mul_f32_e32 v64, 0xbfb8aa3b, v130
	v_mul_f32_e32 v65, 0xbfb8aa3b, v131
	v_exp_f32_e32 v64, v64
	v_exp_f32_e32 v65, v65
	v_pk_mul_f32 v[24:25], v[24:25], v[130:131]
	v_mul_f32_e32 v130, 0xbfb8aa3b, v132
	v_mul_f32_e32 v131, 0xbfb8aa3b, v133
	v_add_f32_e32 v64, 1.0, v64
	v_add_f32_e32 v65, 1.0, v65
	v_rcp_f32_e32 v64, v64
	v_rcp_f32_e32 v65, v65
	v_exp_f32_e32 v130, v130
	v_exp_f32_e32 v131, v131
	v_pk_mul_f32 v[22:23], v[22:23], v[132:133]
	v_pk_mul_f32 v[24:25], v[64:65], v[24:25]
	v_add_f32_e32 v130, 1.0, v130
	v_add_f32_e32 v131, 1.0, v131
	v_rcp_f32_e32 v130, v130
	v_rcp_f32_e32 v131, v131
	v_cvt_pk_bf16_f32 v64, v24, v25
	s_nop 0
	v_pk_mul_f32 v[22:23], v[130:131], v[22:23]
	s_nop 0
	v_cvt_pk_bf16_f32 v65, v22, v23
	global_store_dwordx2 v[46:47], v[64:65], off offset:128
	s_waitcnt vmcnt(9)
	v_lshlrev_b32_e32 v130, 16, v66
	v_and_b32_e32 v131, 0xffff0000, v66
	v_lshlrev_b32_e32 v132, 16, v67
	v_and_b32_e32 v133, 0xffff0000, v67
	v_pk_fma_f32 v[20:21], v[240:241], v[20:21], v[248:249]
	v_pk_fma_f32 v[18:19], v[242:243], v[18:19], v[250:251]
	v_mul_f32_e32 v66, 0xbfb8aa3b, v130
	v_mul_f32_e32 v67, 0xbfb8aa3b, v131
	v_exp_f32_e32 v66, v66
	v_exp_f32_e32 v67, v67
	v_pk_mul_f32 v[20:21], v[20:21], v[130:131]
	v_mul_f32_e32 v130, 0xbfb8aa3b, v132
	v_mul_f32_e32 v131, 0xbfb8aa3b, v133
	v_add_f32_e32 v66, 1.0, v66
	v_add_f32_e32 v67, 1.0, v67
	v_rcp_f32_e32 v66, v66
	v_rcp_f32_e32 v67, v67
	v_exp_f32_e32 v130, v130
	v_exp_f32_e32 v131, v131
	v_pk_mul_f32 v[18:19], v[18:19], v[132:133]
	v_pk_mul_f32 v[20:21], v[66:67], v[20:21]
	v_add_f32_e32 v130, 1.0, v130
	v_add_f32_e32 v131, 1.0, v131
	v_rcp_f32_e32 v130, v130
	v_rcp_f32_e32 v131, v131
	v_cvt_pk_bf16_f32 v66, v20, v21
	s_nop 0
	v_pk_mul_f32 v[18:19], v[130:131], v[18:19]
	s_nop 0
	v_cvt_pk_bf16_f32 v67, v18, v19
	global_store_dwordx2 v[46:47], v[66:67], off offset:160
	s_waitcnt vmcnt(8)
	v_lshlrev_b32_e32 v130, 16, v68
	v_and_b32_e32 v131, 0xffff0000, v68
	v_lshlrev_b32_e32 v132, 16, v69
	v_and_b32_e32 v133, 0xffff0000, v69
	v_pk_fma_f32 v[16:17], v[72:73], v[16:17], v[76:77]
	v_pk_fma_f32 v[14:15], v[74:75], v[14:15], v[78:79]
	v_mul_f32_e32 v68, 0xbfb8aa3b, v130
	v_mul_f32_e32 v69, 0xbfb8aa3b, v131
	v_exp_f32_e32 v68, v68
	v_exp_f32_e32 v69, v69
	v_pk_mul_f32 v[16:17], v[16:17], v[130:131]
	v_mul_f32_e32 v130, 0xbfb8aa3b, v132
	v_mul_f32_e32 v131, 0xbfb8aa3b, v133
	v_add_f32_e32 v68, 1.0, v68
	v_add_f32_e32 v69, 1.0, v69
	v_rcp_f32_e32 v68, v68
	v_rcp_f32_e32 v69, v69
	v_exp_f32_e32 v130, v130
	v_exp_f32_e32 v131, v131
	v_pk_mul_f32 v[14:15], v[14:15], v[132:133]
	v_pk_mul_f32 v[16:17], v[68:69], v[16:17]
	v_add_f32_e32 v130, 1.0, v130
	v_add_f32_e32 v131, 1.0, v131
	v_rcp_f32_e32 v130, v130
	v_rcp_f32_e32 v131, v131
	v_cvt_pk_bf16_f32 v68, v16, v17
	s_nop 0
	v_pk_mul_f32 v[14:15], v[130:131], v[14:15]
	s_nop 0
	v_cvt_pk_bf16_f32 v69, v14, v15
	global_store_dwordx2 v[46:47], v[68:69], off offset:192
	s_waitcnt vmcnt(6)
	v_lshlrev_b32_e32 v130, 16, v70
	v_and_b32_e32 v131, 0xffff0000, v70
	v_lshlrev_b32_e32 v132, 16, v71
	v_and_b32_e32 v133, 0xffff0000, v71
	v_pk_fma_f32 v[10:11], v[80:81], v[10:11], v[84:85]
	v_pk_fma_f32 v[8:9], v[82:83], v[8:9], v[86:87]
	v_mul_f32_e32 v70, 0xbfb8aa3b, v130
	v_mul_f32_e32 v71, 0xbfb8aa3b, v131
	v_exp_f32_e32 v70, v70
	v_exp_f32_e32 v71, v71
	v_pk_mul_f32 v[10:11], v[10:11], v[130:131]
	v_mul_f32_e32 v130, 0xbfb8aa3b, v132
	v_mul_f32_e32 v131, 0xbfb8aa3b, v133
	v_add_f32_e32 v70, 1.0, v70
	v_add_f32_e32 v71, 1.0, v71
	v_rcp_f32_e32 v70, v70
	v_rcp_f32_e32 v71, v71
	v_exp_f32_e32 v130, v130
	v_exp_f32_e32 v131, v131
	v_pk_mul_f32 v[8:9], v[8:9], v[132:133]
	v_pk_mul_f32 v[10:11], v[70:71], v[10:11]
	v_add_f32_e32 v130, 1.0, v130
	v_add_f32_e32 v131, 1.0, v131
	v_rcp_f32_e32 v130, v130
	v_rcp_f32_e32 v131, v131
	v_cvt_pk_bf16_f32 v70, v10, v11
	s_nop 0
	v_pk_mul_f32 v[8:9], v[130:131], v[8:9]
	s_nop 0
	v_cvt_pk_bf16_f32 v71, v8, v9
	global_store_dwordx2 v[46:47], v[70:71], off offset:224
	s_barrier
	s_cbranch_scc1 .LBB0_438
	v_readlane_b32 s82, v255, 40
	v_readlane_b32 s4, v255, 38
	v_readlane_b32 s80, v255, 42
	v_readlane_b32 s83, v255, 41
	v_readlane_b32 s5, v255, 39
	v_readlane_b32 s2, v255, 58
	v_readlane_b32 s81, v255, 43
